# P2/P6/P10 main k-loops: per-segment s_setprio flips removed, one static s_setprio 1 for the older wave half (waves 0-3), as already in P8
# speedup vs baseline: 1.0104x; 1.0013x over previous
.LBB0_368:
	s_and_b32 s16, s8, 3
	s_lshl_b32 s17, s13, 13
	s_lshl_b32 s19, s16, 12
	s_add_u32 s8, s4, 0xa5b8000
	s_mov_b64 s[10:11], 0x80
	s_addc_u32 s9, s5, 0
	s_add_i32 m0, s39, 0x18000
	v_lshl_add_u64 v[8:9], v[8:9], 0, s[10:11]
	s_ashr_i32 s44, s33, 31
	s_waitcnt vmcnt(4)
	s_barrier
	global_load_lds_dwordx4 v[8:9], off
	v_lshl_add_u64 v[6:7], v[6:7], 0, s[10:11]
	s_add_i32 m0, s39, 0x1a000
	s_add_i32 s45, s39, 0x8000
	s_add_i32 s46, s39, 0xa000
	global_load_lds_dwordx4 v[6:7], off
	v_lshl_add_u64 v[4:5], v[4:5], 0, s[10:11]
	s_mov_b32 m0, s45
	s_add_u32 s14, s26, 0x80080
	global_load_lds_dwordx4 v[4:5], off
	v_lshl_add_u64 v[2:3], v[2:3], 0, s[10:11]
	s_mov_b32 m0, s46
	s_addc_u32 s15, s27, 0
	global_load_lds_dwordx4 v[2:3], off
	s_add_i32 m0, s39, 0x1c000
	v_lshl_add_u64 v[2:3], s[14:15], 0, v[130:131]
	global_load_lds_dwordx4 v[2:3], off
	v_lshl_add_u64 v[2:3], s[14:15], 0, v[132:133]
	s_add_i32 m0, s39, 0x1e000
	v_bfe_u32 v4, v10, 4, 2
	global_load_lds_dwordx4 v[2:3], off
	v_and_b32_e32 v3, 15, v10
	v_lshlrev_b32_e32 v2, 4, v4
	v_lshlrev_b32_e32 v6, 2, v10
	v_and_b32_e32 v6, 32, v6
	v_lshl_or_b32 v146, s13, 6, v3
	v_lshl_or_b32 v3, v3, 6, v2
	s_sext_i32_i8 s50, s12
	v_lshlrev_b32_e32 v5, 6, v10
	s_movk_i32 s12, 0x3c0
	v_bitop3_b32 v7, v3, s17, v6 bitop3:0xde
	v_mov_b32_e32 v3, v131
	v_and_or_b32 v5, v5, s12, v2
	v_lshl_add_u64 v[2:3], s[4:5], 0, v[2:3]
	s_mov_b64 s[4:5], 0x62b0000
	v_lshl_add_u64 v[134:135], v[2:3], 0, s[4:5]
	v_lshlrev_b32_e32 v2, 9, v10
	v_and_b32_e32 v2, 0x70000, v2
	v_lshlrev_b32_e32 v3, 12, v13
	v_or3_b32 v2, v11, v2, v3
	v_add_u32_e32 v136, v2, v12
	v_lshlrev_b32_e32 v2, 5, v14
	s_waitcnt vmcnt(6)
	s_cmp_eq_u32 s16, 0
	v_and_b32_e32 v2, 0xf0000, v2
	v_bitop3_b32 v147, s19, v5, v6 bitop3:0xf6
	v_lshlrev_b32_e32 v4, 2, v4
	s_cselect_b64 s[12:13], -1, 0
	v_or3_b32 v2, v11, v2, v3
	s_add_i32 s47, 0, 0x10000
	s_add_i32 s48, 0, 0x14000
	v_and_b32_e32 v144, 4, v4
	v_and_b32_e32 v145, 8, v4
	v_lshlrev_b32_e32 v144, 2, v144
	v_or_b32_e32 v144, v144, v145
	v_lshl_or_b32 v148, s16, 5, v144
	v_mov_b32_e32 v137, v131
	v_add_u32_e32 v138, v2, v12
	v_mov_b32_e32 v139, v131
	v_mov_b64_e32 v[140:141], 0x5ee
	v_mov_b64_e32 v[142:143], 0x5ed
	v_add_u32_e32 v149, s47, v147
	v_add_u32_e32 v150, 0, v7
	v_add_u32_e32 v151, s48, v147
	s_movk_i32 s49, 0x2c00
	s_barrier
	s_cmpk_lt_u32 s34, 0x1000
	s_cbranch_scc0 .Lp2_prio_done
	s_setprio 1
.Lp2_prio_done:
	s_branch .LBB0_370

.LBB0_376:
	v_add_u32_e32 v222, 0x18000, v147
	v_add_u32_e32 v223, 0x1c000, v147
	ds_read_b128 v[152:155], v149
	ds_read_b128 v[156:159], v149 offset:1024
	ds_read_b128 v[160:163], v149 offset:2048
	ds_read_b128 v[168:171], v149 offset:3072
	ds_read_b128 v[172:175], v150
	ds_read_b128 v[176:179], v150 offset:1024
	ds_read_b128 v[180:183], v150 offset:2048
	ds_read_b128 v[184:187], v150 offset:3072
	ds_read_b128 v[188:191], v150 offset:4096
	ds_read_b128 v[192:195], v150 offset:5120
	ds_read_b128 v[196:199], v150 offset:6144
	ds_read_b128 v[200:203], v150 offset:7168
	s_ashr_i32 s17, s16, 31
	v_cmp_lt_i64_e32 vcc, s[20:21], v[140:141]
	s_lshl_b64 s[20:21], s[16:17], 20
	s_add_u32 s20, s35, s20
	s_addc_u32 s21, s36, s21
	s_and_b64 s[22:23], vcc, exec
	s_cselect_b32 s17, s21, s25
	s_cselect_b32 s19, s20, s24
	s_ashr_i32 s15, s14, 31
	s_lshl_b64 s[22:23], s[14:15], 20
	s_add_u32 s22, s37, s22
	s_addc_u32 s23, s38, s23
	s_and_b64 s[28:29], vcc, exec
	s_cselect_b32 s15, s23, s27
	s_cselect_b32 s51, s22, s26
	s_add_u32 s24, s24, 0x80080
	s_addc_u32 s25, s25, 0
	s_add_u32 s52, s26, 0x100
	s_addc_u32 s53, s27, 0
	s_mov_b32 s54, -2
	s_add_u32 s26, s24, 0xfff80080
	s_addc_u32 s27, s25, -1
	s_cmp_eq_u32 s54, 28
	s_cselect_b32 s29, s17, s27
	s_cselect_b32 s28, s19, s26
	s_cselect_b32 s27, s15, s53
	s_cselect_b32 s26, s51, s52
	s_add_i32 m0, s39, 0xc000
	s_nop 0
	global_load_lds_dwordx4 v136, s[24:25]
	s_add_i32 m0, s39, 0xe000
	s_nop 0
	global_load_lds_dwordx4 v138, s[24:25]
	s_waitcnt vmcnt(10)
	s_barrier
	s_waitcnt lgkmcnt(0)
	v_mfma_f32_16x16x32_bf16 v[126:129], v[152:155], v[172:175], 0
	ds_read_b128 v[204:207], v151
	v_mfma_f32_16x16x32_bf16 v[122:125], v[160:163], v[172:175], 0
	v_mfma_f32_16x16x32_bf16 v[118:121], v[152:155], v[180:183], 0
	v_mfma_f32_16x16x32_bf16 v[114:117], v[160:163], v[180:183], 0
	v_mfma_f32_16x16x32_bf16 v[102:105], v[152:155], v[188:191], 0
	ds_read_b128 v[208:211], v151 offset:1024
	v_mfma_f32_16x16x32_bf16 v[98:101], v[160:163], v[188:191], 0
	v_mfma_f32_16x16x32_bf16 v[86:89], v[152:155], v[196:199], 0
	v_mfma_f32_16x16x32_bf16 v[82:85], v[160:163], v[196:199], 0
	v_mfma_f32_16x16x32_bf16 v[126:129], v[156:159], v[176:179], v[126:129]
	ds_read_b128 v[212:215], v151 offset:2048
	v_mfma_f32_16x16x32_bf16 v[122:125], v[168:171], v[176:179], v[122:125]
	v_mfma_f32_16x16x32_bf16 v[118:121], v[156:159], v[184:187], v[118:121]
	v_mfma_f32_16x16x32_bf16 v[114:117], v[168:171], v[184:187], v[114:117]
	v_mfma_f32_16x16x32_bf16 v[102:105], v[156:159], v[192:195], v[102:105]
	ds_read_b128 v[216:219], v151 offset:3072
	v_mfma_f32_16x16x32_bf16 v[98:101], v[168:171], v[192:195], v[98:101]
	v_mfma_f32_16x16x32_bf16 v[86:89], v[156:159], v[200:203], v[86:89]
	v_mfma_f32_16x16x32_bf16 v[82:85], v[168:171], v[200:203], v[82:85]
	s_barrier
	s_add_i32 s55, s47, s34
	s_add_u32 s96, s26, 0x80
	s_addc_u32 s97, s27, 0
	s_mov_b32 m0, s55
	s_nop 0
	global_load_lds_dwordx4 v130, s[26:27]
	s_add_i32 m0, s55, 0x2000
	s_nop 0
	global_load_lds_dwordx4 v132, s[26:27]
	s_waitcnt vmcnt(10)
	s_barrier
	s_waitcnt lgkmcnt(0)
	v_mfma_f32_16x16x32_bf16 v[110:113], v[204:207], v[172:175], 0
	ds_read_b128 v[224:227], v150 offset:16384
	v_mfma_f32_16x16x32_bf16 v[106:109], v[212:215], v[172:175], 0
	v_mfma_f32_16x16x32_bf16 v[94:97], v[204:207], v[180:183], 0
	ds_read_b128 v[228:231], v150 offset:17408
	v_mfma_f32_16x16x32_bf16 v[90:93], v[212:215], v[180:183], 0
	v_mfma_f32_16x16x32_bf16 v[78:81], v[204:207], v[188:191], 0
	ds_read_b128 v[232:235], v150 offset:18432
	v_mfma_f32_16x16x32_bf16 v[74:77], v[212:215], v[188:191], 0
	v_mfma_f32_16x16x32_bf16 v[70:73], v[204:207], v[196:199], 0
	ds_read_b128 v[236:239], v150 offset:19456
	v_mfma_f32_16x16x32_bf16 v[66:69], v[212:215], v[196:199], 0
	v_mfma_f32_16x16x32_bf16 v[110:113], v[208:211], v[176:179], v[110:113]
	ds_read_b128 v[240:243], v150 offset:20480
	v_mfma_f32_16x16x32_bf16 v[106:109], v[216:219], v[176:179], v[106:109]
	v_mfma_f32_16x16x32_bf16 v[94:97], v[208:211], v[184:187], v[94:97]
	ds_read_b128 v[244:247], v150 offset:21504
	v_mfma_f32_16x16x32_bf16 v[90:93], v[216:219], v[184:187], v[90:93]
	v_mfma_f32_16x16x32_bf16 v[78:81], v[208:211], v[192:195], v[78:81]
	ds_read_b128 v[248:251], v150 offset:22528
	v_mfma_f32_16x16x32_bf16 v[74:77], v[216:219], v[192:195], v[74:77]
	v_mfma_f32_16x16x32_bf16 v[70:73], v[208:211], v[200:203], v[70:73]
	ds_read_b128 v[164:167], v150 offset:23552
	v_mfma_f32_16x16x32_bf16 v[66:69], v[216:219], v[200:203], v[66:69]
	s_barrier
	s_mov_b32 m0, s39
	s_add_u32 s94, s28, 0x80
	s_addc_u32 s95, s29, 0
	global_load_lds_dwordx4 v130, s[28:29]
	s_mov_b32 m0, s40
	s_nop 0
	global_load_lds_dwordx4 v132, s[28:29]
	s_waitcnt vmcnt(8)
	s_barrier
	s_waitcnt lgkmcnt(0)
	v_mfma_f32_16x16x32_bf16 v[62:65], v[152:155], v[224:227], 0
	ds_read_b128 v[172:175], v150 offset:32768
	v_mfma_f32_16x16x32_bf16 v[58:61], v[160:163], v[224:227], 0
	v_mfma_f32_16x16x32_bf16 v[54:57], v[152:155], v[232:235], 0
	ds_read_b128 v[176:179], v150 offset:33792
	v_mfma_f32_16x16x32_bf16 v[50:53], v[160:163], v[232:235], 0
	v_mfma_f32_16x16x32_bf16 v[38:41], v[152:155], v[240:243], 0
	ds_read_b128 v[180:183], v150 offset:34816
	v_mfma_f32_16x16x32_bf16 v[34:37], v[160:163], v[240:243], 0
	v_mfma_f32_16x16x32_bf16 v[22:25], v[152:155], v[248:251], 0
	ds_read_b128 v[184:187], v150 offset:35840
	v_mfma_f32_16x16x32_bf16 v[18:21], v[160:163], v[248:251], 0
	v_mfma_f32_16x16x32_bf16 v[62:65], v[156:159], v[228:231], v[62:65]
	ds_read_b128 v[188:191], v150 offset:36864
	v_mfma_f32_16x16x32_bf16 v[58:61], v[168:171], v[228:231], v[58:61]
	v_mfma_f32_16x16x32_bf16 v[54:57], v[156:159], v[236:239], v[54:57]
	ds_read_b128 v[192:195], v150 offset:37888
	v_mfma_f32_16x16x32_bf16 v[50:53], v[168:171], v[236:239], v[50:53]
	v_mfma_f32_16x16x32_bf16 v[38:41], v[156:159], v[244:247], v[38:41]
	ds_read_b128 v[196:199], v150 offset:38912
	v_mfma_f32_16x16x32_bf16 v[34:37], v[168:171], v[244:247], v[34:37]
	v_mfma_f32_16x16x32_bf16 v[22:25], v[156:159], v[164:167], v[22:25]
	ds_read_b128 v[200:203], v150 offset:39936
	v_mfma_f32_16x16x32_bf16 v[18:21], v[168:171], v[164:167], v[18:21]
	s_barrier
	s_add_u32 s56, s26, 0x80000
	s_addc_u32 s57, s27, 0
	s_add_i32 s55, s48, s34
	s_mov_b32 m0, s55
	s_nop 0
	global_load_lds_dwordx4 v130, s[56:57]
	s_add_i32 m0, s55, 0x2000
	s_nop 0
	global_load_lds_dwordx4 v132, s[56:57]
	s_waitcnt vmcnt(10)
	s_barrier
	s_waitcnt lgkmcnt(0)
	v_mfma_f32_16x16x32_bf16 v[46:49], v[204:207], v[224:227], 0
	ds_read_b128 v[152:155], v222
	v_mfma_f32_16x16x32_bf16 v[42:45], v[212:215], v[224:227], 0
	v_mfma_f32_16x16x32_bf16 v[30:33], v[204:207], v[232:235], 0
	v_mfma_f32_16x16x32_bf16 v[26:29], v[212:215], v[232:235], 0
	v_mfma_f32_16x16x32_bf16 v[14:17], v[204:207], v[240:243], 0
	ds_read_b128 v[156:159], v222 offset:1024
	v_mfma_f32_16x16x32_bf16 v[10:13], v[212:215], v[240:243], 0
	v_mfma_f32_16x16x32_bf16 v[6:9], v[204:207], v[248:251], 0
	v_mfma_f32_16x16x32_bf16 v[2:5], v[212:215], v[248:251], 0
	v_mfma_f32_16x16x32_bf16 v[46:49], v[208:211], v[228:231], v[46:49]
	ds_read_b128 v[160:163], v222 offset:2048
	v_mfma_f32_16x16x32_bf16 v[42:45], v[216:219], v[228:231], v[42:45]
	v_mfma_f32_16x16x32_bf16 v[30:33], v[208:211], v[236:239], v[30:33]
	v_mfma_f32_16x16x32_bf16 v[26:29], v[216:219], v[236:239], v[26:29]
	v_mfma_f32_16x16x32_bf16 v[14:17], v[208:211], v[244:247], v[14:17]
	ds_read_b128 v[168:171], v222 offset:3072
	v_mfma_f32_16x16x32_bf16 v[10:13], v[216:219], v[244:247], v[10:13]
	v_mfma_f32_16x16x32_bf16 v[6:9], v[208:211], v[164:167], v[6:9]
	v_mfma_f32_16x16x32_bf16 v[2:5], v[216:219], v[164:167], v[2:5]
	s_barrier
	s_add_i32 s55, 0, 0x18000
	s_add_u32 s28, s28, 0x80000
	s_addc_u32 s29, s29, 0
	s_mov_b32 m0, s41
	s_nop 0
	global_load_lds_dwordx4 v130, s[28:29]
	s_mov_b32 m0, s42
	s_nop 0
	global_load_lds_dwordx4 v132, s[28:29]
	s_waitcnt vmcnt(10)
	s_barrier
	s_waitcnt lgkmcnt(0)
	v_mfma_f32_16x16x32_bf16 v[126:129], v[152:155], v[172:175], v[126:129]
	ds_read_b128 v[204:207], v223
	v_mfma_f32_16x16x32_bf16 v[122:125], v[160:163], v[172:175], v[122:125]
	v_mfma_f32_16x16x32_bf16 v[118:121], v[152:155], v[180:183], v[118:121]
	v_mfma_f32_16x16x32_bf16 v[114:117], v[160:163], v[180:183], v[114:117]
	v_mfma_f32_16x16x32_bf16 v[102:105], v[152:155], v[188:191], v[102:105]
	ds_read_b128 v[208:211], v223 offset:1024
	v_mfma_f32_16x16x32_bf16 v[98:101], v[160:163], v[188:191], v[98:101]
	v_mfma_f32_16x16x32_bf16 v[86:89], v[152:155], v[196:199], v[86:89]
	v_mfma_f32_16x16x32_bf16 v[82:85], v[160:163], v[196:199], v[82:85]
	v_mfma_f32_16x16x32_bf16 v[126:129], v[156:159], v[176:179], v[126:129]
	ds_read_b128 v[212:215], v223 offset:2048
	v_mfma_f32_16x16x32_bf16 v[122:125], v[168:171], v[176:179], v[122:125]
	v_mfma_f32_16x16x32_bf16 v[118:121], v[156:159], v[184:187], v[118:121]
	v_mfma_f32_16x16x32_bf16 v[114:117], v[168:171], v[184:187], v[114:117]
	v_mfma_f32_16x16x32_bf16 v[102:105], v[156:159], v[192:195], v[102:105]
	ds_read_b128 v[216:219], v223 offset:3072
	v_mfma_f32_16x16x32_bf16 v[98:101], v[168:171], v[192:195], v[98:101]
	v_mfma_f32_16x16x32_bf16 v[86:89], v[156:159], v[200:203], v[86:89]
	v_mfma_f32_16x16x32_bf16 v[82:85], v[168:171], v[200:203], v[82:85]
	s_barrier
	s_add_i32 s84, 0, 0x1c000
	s_add_i32 s85, s55, s34
	s_mov_b32 m0, s85
	s_nop 0
	global_load_lds_dwordx4 v130, s[96:97]
	s_add_i32 m0, s85, 0x2000
	s_nop 0
	global_load_lds_dwordx4 v132, s[96:97]
	s_waitcnt vmcnt(10)
	s_barrier
	s_waitcnt lgkmcnt(0)
	v_mfma_f32_16x16x32_bf16 v[110:113], v[204:207], v[172:175], v[110:113]
	ds_read_b128 v[224:227], v150 offset:49152
	v_mfma_f32_16x16x32_bf16 v[106:109], v[212:215], v[172:175], v[106:109]
	v_mfma_f32_16x16x32_bf16 v[94:97], v[204:207], v[180:183], v[94:97]
	ds_read_b128 v[228:231], v150 offset:50176
	v_mfma_f32_16x16x32_bf16 v[90:93], v[212:215], v[180:183], v[90:93]
	v_mfma_f32_16x16x32_bf16 v[78:81], v[204:207], v[188:191], v[78:81]
	ds_read_b128 v[232:235], v150 offset:51200
	v_mfma_f32_16x16x32_bf16 v[74:77], v[212:215], v[188:191], v[74:77]
	v_mfma_f32_16x16x32_bf16 v[70:73], v[204:207], v[196:199], v[70:73]
	ds_read_b128 v[236:239], v150 offset:52224
	v_mfma_f32_16x16x32_bf16 v[66:69], v[212:215], v[196:199], v[66:69]
	v_mfma_f32_16x16x32_bf16 v[110:113], v[208:211], v[176:179], v[110:113]
	ds_read_b128 v[240:243], v150 offset:53248
	v_mfma_f32_16x16x32_bf16 v[106:109], v[216:219], v[176:179], v[106:109]
	v_mfma_f32_16x16x32_bf16 v[94:97], v[208:211], v[184:187], v[94:97]
	ds_read_b128 v[244:247], v150 offset:54272
	v_mfma_f32_16x16x32_bf16 v[90:93], v[216:219], v[184:187], v[90:93]
	v_mfma_f32_16x16x32_bf16 v[78:81], v[208:211], v[192:195], v[78:81]
	ds_read_b128 v[248:251], v150 offset:55296
	v_mfma_f32_16x16x32_bf16 v[74:77], v[216:219], v[192:195], v[74:77]
	v_mfma_f32_16x16x32_bf16 v[70:73], v[208:211], v[200:203], v[70:73]
	ds_read_b128 v[164:167], v150 offset:56320
	v_mfma_f32_16x16x32_bf16 v[66:69], v[216:219], v[200:203], v[66:69]
	s_barrier
	s_mov_b32 m0, s45
	s_nop 0
	global_load_lds_dwordx4 v130, s[94:95]
	s_mov_b32 m0, s46
	s_nop 0
	global_load_lds_dwordx4 v132, s[94:95]
	s_waitcnt vmcnt(8)
	s_barrier
	s_waitcnt lgkmcnt(0)
	v_mfma_f32_16x16x32_bf16 v[62:65], v[152:155], v[224:227], v[62:65]
	ds_read_b128 v[172:175], v150
	v_mfma_f32_16x16x32_bf16 v[58:61], v[160:163], v[224:227], v[58:61]
	v_mfma_f32_16x16x32_bf16 v[54:57], v[152:155], v[232:235], v[54:57]
	ds_read_b128 v[176:179], v150 offset:1024
	v_mfma_f32_16x16x32_bf16 v[50:53], v[160:163], v[232:235], v[50:53]
	v_mfma_f32_16x16x32_bf16 v[38:41], v[152:155], v[240:243], v[38:41]
	ds_read_b128 v[180:183], v150 offset:2048
	v_mfma_f32_16x16x32_bf16 v[34:37], v[160:163], v[240:243], v[34:37]
	v_mfma_f32_16x16x32_bf16 v[22:25], v[152:155], v[248:251], v[22:25]
	ds_read_b128 v[184:187], v150 offset:3072
	v_mfma_f32_16x16x32_bf16 v[18:21], v[160:163], v[248:251], v[18:21]
	v_mfma_f32_16x16x32_bf16 v[62:65], v[156:159], v[228:231], v[62:65]
	ds_read_b128 v[188:191], v150 offset:4096
	v_mfma_f32_16x16x32_bf16 v[58:61], v[168:171], v[228:231], v[58:61]
	v_mfma_f32_16x16x32_bf16 v[54:57], v[156:159], v[236:239], v[54:57]
	ds_read_b128 v[192:195], v150 offset:5120
	v_mfma_f32_16x16x32_bf16 v[50:53], v[168:171], v[236:239], v[50:53]
	v_mfma_f32_16x16x32_bf16 v[38:41], v[156:159], v[244:247], v[38:41]
	ds_read_b128 v[196:199], v150 offset:6144
	v_mfma_f32_16x16x32_bf16 v[34:37], v[168:171], v[244:247], v[34:37]
	v_mfma_f32_16x16x32_bf16 v[22:25], v[156:159], v[164:167], v[22:25]
	ds_read_b128 v[200:203], v150 offset:7168
	v_mfma_f32_16x16x32_bf16 v[18:21], v[168:171], v[164:167], v[18:21]
	s_barrier
	s_add_u32 s26, s26, 0x80080
	s_addc_u32 s27, s27, 0
	s_add_i32 s84, s84, s34
	s_mov_b32 m0, s84
	s_nop 0
	global_load_lds_dwordx4 v130, s[26:27]
	s_add_i32 m0, s84, 0x2000
	s_nop 0
	global_load_lds_dwordx4 v132, s[26:27]
	s_waitcnt vmcnt(10)
	s_barrier
	s_waitcnt lgkmcnt(0)
	v_mfma_f32_16x16x32_bf16 v[46:49], v[204:207], v[224:227], v[46:49]
	ds_read_b128 v[152:155], v149
	v_mfma_f32_16x16x32_bf16 v[42:45], v[212:215], v[224:227], v[42:45]
	v_mfma_f32_16x16x32_bf16 v[30:33], v[204:207], v[232:235], v[30:33]
	v_mfma_f32_16x16x32_bf16 v[26:29], v[212:215], v[232:235], v[26:29]
	v_mfma_f32_16x16x32_bf16 v[14:17], v[204:207], v[240:243], v[14:17]
	ds_read_b128 v[156:159], v149 offset:1024
	v_mfma_f32_16x16x32_bf16 v[10:13], v[212:215], v[240:243], v[10:13]
	v_mfma_f32_16x16x32_bf16 v[6:9], v[204:207], v[248:251], v[6:9]
	v_mfma_f32_16x16x32_bf16 v[2:5], v[212:215], v[248:251], v[2:5]
	v_mfma_f32_16x16x32_bf16 v[46:49], v[208:211], v[228:231], v[46:49]
	ds_read_b128 v[160:163], v149 offset:2048
	v_mfma_f32_16x16x32_bf16 v[42:45], v[216:219], v[228:231], v[42:45]
	v_mfma_f32_16x16x32_bf16 v[30:33], v[208:211], v[236:239], v[30:33]
	v_mfma_f32_16x16x32_bf16 v[26:29], v[216:219], v[236:239], v[26:29]
	v_mfma_f32_16x16x32_bf16 v[14:17], v[208:211], v[244:247], v[14:17]
	ds_read_b128 v[168:171], v149 offset:3072
	v_mfma_f32_16x16x32_bf16 v[10:13], v[216:219], v[244:247], v[10:13]
	v_mfma_f32_16x16x32_bf16 v[6:9], v[208:211], v[164:167], v[6:9]
	v_mfma_f32_16x16x32_bf16 v[2:5], v[216:219], v[164:167], v[2:5]
	s_add_i32 s54, s54, 2
	s_add_u32 s24, s24, 0x100
	s_addc_u32 s25, s25, 0
	s_add_u32 s52, s52, 0x100
	s_addc_u32 s53, s53, 0
	s_cmp_gt_u32 s54, 29
	s_barrier
	s_cbranch_scc0 .LBB0_377
	s_branch .Lp2_loop_exit
.LBB0_377:
	s_add_u32 s26, s24, 0xfff80080
	s_addc_u32 s27, s25, -1
	s_cmp_eq_u32 s54, 28
	s_cselect_b32 s29, s17, s27
	s_cselect_b32 s28, s19, s26
	s_cselect_b32 s27, s15, s53
	s_cselect_b32 s26, s51, s52
	s_add_i32 m0, s39, 0xc000
	s_nop 0
	global_load_lds_dwordx4 v136, s[24:25]
	s_add_i32 m0, s39, 0xe000
	s_nop 0
	global_load_lds_dwordx4 v138, s[24:25]
	s_waitcnt vmcnt(10)
	s_barrier
	s_waitcnt lgkmcnt(0)
	v_mfma_f32_16x16x32_bf16 v[126:129], v[152:155], v[172:175], v[126:129]
	ds_read_b128 v[204:207], v151
	v_mfma_f32_16x16x32_bf16 v[122:125], v[160:163], v[172:175], v[122:125]
	v_mfma_f32_16x16x32_bf16 v[118:121], v[152:155], v[180:183], v[118:121]
	v_mfma_f32_16x16x32_bf16 v[114:117], v[160:163], v[180:183], v[114:117]
	v_mfma_f32_16x16x32_bf16 v[102:105], v[152:155], v[188:191], v[102:105]
	ds_read_b128 v[208:211], v151 offset:1024
	v_mfma_f32_16x16x32_bf16 v[98:101], v[160:163], v[188:191], v[98:101]
	v_mfma_f32_16x16x32_bf16 v[86:89], v[152:155], v[196:199], v[86:89]
	v_mfma_f32_16x16x32_bf16 v[82:85], v[160:163], v[196:199], v[82:85]
	v_mfma_f32_16x16x32_bf16 v[126:129], v[156:159], v[176:179], v[126:129]
	ds_read_b128 v[212:215], v151 offset:2048
	v_mfma_f32_16x16x32_bf16 v[122:125], v[168:171], v[176:179], v[122:125]
	v_mfma_f32_16x16x32_bf16 v[118:121], v[156:159], v[184:187], v[118:121]
	v_mfma_f32_16x16x32_bf16 v[114:117], v[168:171], v[184:187], v[114:117]
	v_mfma_f32_16x16x32_bf16 v[102:105], v[156:159], v[192:195], v[102:105]
	ds_read_b128 v[216:219], v151 offset:3072
	v_mfma_f32_16x16x32_bf16 v[98:101], v[168:171], v[192:195], v[98:101]
	v_mfma_f32_16x16x32_bf16 v[86:89], v[156:159], v[200:203], v[86:89]
	v_mfma_f32_16x16x32_bf16 v[82:85], v[168:171], v[200:203], v[82:85]
	s_barrier
	s_add_i32 s55, s47, s34
	s_add_u32 s96, s26, 0x80
	s_addc_u32 s97, s27, 0
	s_mov_b32 m0, s55
	s_nop 0
	global_load_lds_dwordx4 v130, s[26:27]
	s_add_i32 m0, s55, 0x2000
	s_nop 0
	global_load_lds_dwordx4 v132, s[26:27]
	s_waitcnt vmcnt(10)
	s_barrier
	s_waitcnt lgkmcnt(0)
	v_mfma_f32_16x16x32_bf16 v[110:113], v[204:207], v[172:175], v[110:113]
	ds_read_b128 v[224:227], v150 offset:16384
	v_mfma_f32_16x16x32_bf16 v[106:109], v[212:215], v[172:175], v[106:109]
	v_mfma_f32_16x16x32_bf16 v[94:97], v[204:207], v[180:183], v[94:97]
	ds_read_b128 v[228:231], v150 offset:17408
	v_mfma_f32_16x16x32_bf16 v[90:93], v[212:215], v[180:183], v[90:93]
	v_mfma_f32_16x16x32_bf16 v[78:81], v[204:207], v[188:191], v[78:81]
	ds_read_b128 v[232:235], v150 offset:18432
	v_mfma_f32_16x16x32_bf16 v[74:77], v[212:215], v[188:191], v[74:77]
	v_mfma_f32_16x16x32_bf16 v[70:73], v[204:207], v[196:199], v[70:73]
	ds_read_b128 v[236:239], v150 offset:19456
	v_mfma_f32_16x16x32_bf16 v[66:69], v[212:215], v[196:199], v[66:69]
	v_mfma_f32_16x16x32_bf16 v[110:113], v[208:211], v[176:179], v[110:113]
	ds_read_b128 v[240:243], v150 offset:20480
	v_mfma_f32_16x16x32_bf16 v[106:109], v[216:219], v[176:179], v[106:109]
	v_mfma_f32_16x16x32_bf16 v[94:97], v[208:211], v[184:187], v[94:97]
	ds_read_b128 v[244:247], v150 offset:21504
	v_mfma_f32_16x16x32_bf16 v[90:93], v[216:219], v[184:187], v[90:93]
	v_mfma_f32_16x16x32_bf16 v[78:81], v[208:211], v[192:195], v[78:81]
	ds_read_b128 v[248:251], v150 offset:22528
	v_mfma_f32_16x16x32_bf16 v[74:77], v[216:219], v[192:195], v[74:77]
	v_mfma_f32_16x16x32_bf16 v[70:73], v[208:211], v[200:203], v[70:73]
	ds_read_b128 v[164:167], v150 offset:23552
	v_mfma_f32_16x16x32_bf16 v[66:69], v[216:219], v[200:203], v[66:69]
	s_barrier
	s_mov_b32 m0, s39
	s_add_u32 s94, s28, 0x80
	s_addc_u32 s95, s29, 0
	global_load_lds_dwordx4 v130, s[28:29]
	s_mov_b32 m0, s40
	s_nop 0
	global_load_lds_dwordx4 v132, s[28:29]
	s_waitcnt vmcnt(8)
	s_barrier
	s_waitcnt lgkmcnt(0)
	v_mfma_f32_16x16x32_bf16 v[62:65], v[152:155], v[224:227], v[62:65]
	ds_read_b128 v[172:175], v150 offset:32768
	v_mfma_f32_16x16x32_bf16 v[58:61], v[160:163], v[224:227], v[58:61]
	v_mfma_f32_16x16x32_bf16 v[54:57], v[152:155], v[232:235], v[54:57]
	ds_read_b128 v[176:179], v150 offset:33792
	v_mfma_f32_16x16x32_bf16 v[50:53], v[160:163], v[232:235], v[50:53]
	v_mfma_f32_16x16x32_bf16 v[38:41], v[152:155], v[240:243], v[38:41]
	ds_read_b128 v[180:183], v150 offset:34816
	v_mfma_f32_16x16x32_bf16 v[34:37], v[160:163], v[240:243], v[34:37]
	v_mfma_f32_16x16x32_bf16 v[22:25], v[152:155], v[248:251], v[22:25]
	ds_read_b128 v[184:187], v150 offset:35840
	v_mfma_f32_16x16x32_bf16 v[18:21], v[160:163], v[248:251], v[18:21]
	v_mfma_f32_16x16x32_bf16 v[62:65], v[156:159], v[228:231], v[62:65]
	ds_read_b128 v[188:191], v150 offset:36864
	v_mfma_f32_16x16x32_bf16 v[58:61], v[168:171], v[228:231], v[58:61]
	v_mfma_f32_16x16x32_bf16 v[54:57], v[156:159], v[236:239], v[54:57]
	ds_read_b128 v[192:195], v150 offset:37888
	v_mfma_f32_16x16x32_bf16 v[50:53], v[168:171], v[236:239], v[50:53]
	v_mfma_f32_16x16x32_bf16 v[38:41], v[156:159], v[244:247], v[38:41]
	ds_read_b128 v[196:199], v150 offset:38912
	v_mfma_f32_16x16x32_bf16 v[34:37], v[168:171], v[244:247], v[34:37]
	v_mfma_f32_16x16x32_bf16 v[22:25], v[156:159], v[164:167], v[22:25]
	ds_read_b128 v[200:203], v150 offset:39936
	v_mfma_f32_16x16x32_bf16 v[18:21], v[168:171], v[164:167], v[18:21]
	s_barrier
	s_add_u32 s56, s26, 0x80000
	s_addc_u32 s57, s27, 0
	s_add_i32 s55, s48, s34
	s_mov_b32 m0, s55
	s_nop 0
	global_load_lds_dwordx4 v130, s[56:57]
	s_add_i32 m0, s55, 0x2000
	s_nop 0
	global_load_lds_dwordx4 v132, s[56:57]
	s_waitcnt vmcnt(10)
	s_barrier
	s_waitcnt lgkmcnt(0)
	v_mfma_f32_16x16x32_bf16 v[46:49], v[204:207], v[224:227], v[46:49]
	ds_read_b128 v[152:155], v222
	v_mfma_f32_16x16x32_bf16 v[42:45], v[212:215], v[224:227], v[42:45]
	v_mfma_f32_16x16x32_bf16 v[30:33], v[204:207], v[232:235], v[30:33]
	v_mfma_f32_16x16x32_bf16 v[26:29], v[212:215], v[232:235], v[26:29]
	v_mfma_f32_16x16x32_bf16 v[14:17], v[204:207], v[240:243], v[14:17]
	ds_read_b128 v[156:159], v222 offset:1024
	v_mfma_f32_16x16x32_bf16 v[10:13], v[212:215], v[240:243], v[10:13]
	v_mfma_f32_16x16x32_bf16 v[6:9], v[204:207], v[248:251], v[6:9]
	v_mfma_f32_16x16x32_bf16 v[2:5], v[212:215], v[248:251], v[2:5]
	v_mfma_f32_16x16x32_bf16 v[46:49], v[208:211], v[228:231], v[46:49]
	ds_read_b128 v[160:163], v222 offset:2048
	v_mfma_f32_16x16x32_bf16 v[42:45], v[216:219], v[228:231], v[42:45]
	v_mfma_f32_16x16x32_bf16 v[30:33], v[208:211], v[236:239], v[30:33]
	v_mfma_f32_16x16x32_bf16 v[26:29], v[216:219], v[236:239], v[26:29]
	v_mfma_f32_16x16x32_bf16 v[14:17], v[208:211], v[244:247], v[14:17]
	ds_read_b128 v[168:171], v222 offset:3072
	v_mfma_f32_16x16x32_bf16 v[10:13], v[216:219], v[244:247], v[10:13]
	v_mfma_f32_16x16x32_bf16 v[6:9], v[208:211], v[164:167], v[6:9]
	v_mfma_f32_16x16x32_bf16 v[2:5], v[216:219], v[164:167], v[2:5]
	s_barrier
	s_add_i32 s55, 0, 0x18000
	s_add_u32 s28, s28, 0x80000
	s_addc_u32 s29, s29, 0
	s_mov_b32 m0, s41
	s_nop 0
	global_load_lds_dwordx4 v130, s[28:29]
	s_mov_b32 m0, s42
	s_nop 0
	global_load_lds_dwordx4 v132, s[28:29]
	s_waitcnt vmcnt(10)
	s_barrier
	s_waitcnt lgkmcnt(0)
	v_mfma_f32_16x16x32_bf16 v[126:129], v[152:155], v[172:175], v[126:129]
	ds_read_b128 v[204:207], v223
	v_mfma_f32_16x16x32_bf16 v[122:125], v[160:163], v[172:175], v[122:125]
	v_mfma_f32_16x16x32_bf16 v[118:121], v[152:155], v[180:183], v[118:121]
	v_mfma_f32_16x16x32_bf16 v[114:117], v[160:163], v[180:183], v[114:117]
	v_mfma_f32_16x16x32_bf16 v[102:105], v[152:155], v[188:191], v[102:105]
	ds_read_b128 v[208:211], v223 offset:1024
	v_mfma_f32_16x16x32_bf16 v[98:101], v[160:163], v[188:191], v[98:101]
	v_mfma_f32_16x16x32_bf16 v[86:89], v[152:155], v[196:199], v[86:89]
	v_mfma_f32_16x16x32_bf16 v[82:85], v[160:163], v[196:199], v[82:85]
	v_mfma_f32_16x16x32_bf16 v[126:129], v[156:159], v[176:179], v[126:129]
	ds_read_b128 v[212:215], v223 offset:2048
	v_mfma_f32_16x16x32_bf16 v[122:125], v[168:171], v[176:179], v[122:125]
	v_mfma_f32_16x16x32_bf16 v[118:121], v[156:159], v[184:187], v[118:121]
	v_mfma_f32_16x16x32_bf16 v[114:117], v[168:171], v[184:187], v[114:117]
	v_mfma_f32_16x16x32_bf16 v[102:105], v[156:159], v[192:195], v[102:105]
	ds_read_b128 v[216:219], v223 offset:3072
	v_mfma_f32_16x16x32_bf16 v[98:101], v[168:171], v[192:195], v[98:101]
	v_mfma_f32_16x16x32_bf16 v[86:89], v[156:159], v[200:203], v[86:89]
	v_mfma_f32_16x16x32_bf16 v[82:85], v[168:171], v[200:203], v[82:85]
	s_barrier
	s_add_i32 s84, 0, 0x1c000
	s_add_i32 s85, s55, s34
	s_mov_b32 m0, s85
	s_nop 0
	global_load_lds_dwordx4 v130, s[96:97]
	s_add_i32 m0, s85, 0x2000
	s_nop 0
	global_load_lds_dwordx4 v132, s[96:97]
	s_waitcnt vmcnt(10)
	s_barrier
	s_waitcnt lgkmcnt(0)
	v_mfma_f32_16x16x32_bf16 v[110:113], v[204:207], v[172:175], v[110:113]
	ds_read_b128 v[224:227], v150 offset:49152
	v_mfma_f32_16x16x32_bf16 v[106:109], v[212:215], v[172:175], v[106:109]
	v_mfma_f32_16x16x32_bf16 v[94:97], v[204:207], v[180:183], v[94:97]
	ds_read_b128 v[228:231], v150 offset:50176
	v_mfma_f32_16x16x32_bf16 v[90:93], v[212:215], v[180:183], v[90:93]
	v_mfma_f32_16x16x32_bf16 v[78:81], v[204:207], v[188:191], v[78:81]
	ds_read_b128 v[232:235], v150 offset:51200
	v_mfma_f32_16x16x32_bf16 v[74:77], v[212:215], v[188:191], v[74:77]
	v_mfma_f32_16x16x32_bf16 v[70:73], v[204:207], v[196:199], v[70:73]
	ds_read_b128 v[236:239], v150 offset:52224
	v_mfma_f32_16x16x32_bf16 v[66:69], v[212:215], v[196:199], v[66:69]
	v_mfma_f32_16x16x32_bf16 v[110:113], v[208:211], v[176:179], v[110:113]
	ds_read_b128 v[240:243], v150 offset:53248
	v_mfma_f32_16x16x32_bf16 v[106:109], v[216:219], v[176:179], v[106:109]
	v_mfma_f32_16x16x32_bf16 v[94:97], v[208:211], v[184:187], v[94:97]
	ds_read_b128 v[244:247], v150 offset:54272
	v_mfma_f32_16x16x32_bf16 v[90:93], v[216:219], v[184:187], v[90:93]
	v_mfma_f32_16x16x32_bf16 v[78:81], v[208:211], v[192:195], v[78:81]
	ds_read_b128 v[248:251], v150 offset:55296
	v_mfma_f32_16x16x32_bf16 v[74:77], v[216:219], v[192:195], v[74:77]
	v_mfma_f32_16x16x32_bf16 v[70:73], v[208:211], v[200:203], v[70:73]
	ds_read_b128 v[164:167], v150 offset:56320
	v_mfma_f32_16x16x32_bf16 v[66:69], v[216:219], v[200:203], v[66:69]
	s_barrier
	s_mov_b32 m0, s45
	s_nop 0
	global_load_lds_dwordx4 v130, s[94:95]
	s_mov_b32 m0, s46
	s_nop 0
	global_load_lds_dwordx4 v132, s[94:95]
	s_waitcnt vmcnt(8)
	s_barrier
	s_waitcnt lgkmcnt(0)
	v_mfma_f32_16x16x32_bf16 v[62:65], v[152:155], v[224:227], v[62:65]
	ds_read_b128 v[172:175], v150
	v_mfma_f32_16x16x32_bf16 v[58:61], v[160:163], v[224:227], v[58:61]
	v_mfma_f32_16x16x32_bf16 v[54:57], v[152:155], v[232:235], v[54:57]
	ds_read_b128 v[176:179], v150 offset:1024
	v_mfma_f32_16x16x32_bf16 v[50:53], v[160:163], v[232:235], v[50:53]
	v_mfma_f32_16x16x32_bf16 v[38:41], v[152:155], v[240:243], v[38:41]
	ds_read_b128 v[180:183], v150 offset:2048
	v_mfma_f32_16x16x32_bf16 v[34:37], v[160:163], v[240:243], v[34:37]
	v_mfma_f32_16x16x32_bf16 v[22:25], v[152:155], v[248:251], v[22:25]
	ds_read_b128 v[184:187], v150 offset:3072
	v_mfma_f32_16x16x32_bf16 v[18:21], v[160:163], v[248:251], v[18:21]
	v_mfma_f32_16x16x32_bf16 v[62:65], v[156:159], v[228:231], v[62:65]
	ds_read_b128 v[188:191], v150 offset:4096
	v_mfma_f32_16x16x32_bf16 v[58:61], v[168:171], v[228:231], v[58:61]
	v_mfma_f32_16x16x32_bf16 v[54:57], v[156:159], v[236:239], v[54:57]
	ds_read_b128 v[192:195], v150 offset:5120
	v_mfma_f32_16x16x32_bf16 v[50:53], v[168:171], v[236:239], v[50:53]
	v_mfma_f32_16x16x32_bf16 v[38:41], v[156:159], v[244:247], v[38:41]
	ds_read_b128 v[196:199], v150 offset:6144
	v_mfma_f32_16x16x32_bf16 v[34:37], v[168:171], v[244:247], v[34:37]
	v_mfma_f32_16x16x32_bf16 v[22:25], v[156:159], v[164:167], v[22:25]
	ds_read_b128 v[200:203], v150 offset:7168
	v_mfma_f32_16x16x32_bf16 v[18:21], v[168:171], v[164:167], v[18:21]
	s_barrier
	s_add_u32 s26, s26, 0x80080
	s_addc_u32 s27, s27, 0
	s_add_i32 s84, s84, s34
	s_mov_b32 m0, s84
	s_nop 0
	global_load_lds_dwordx4 v130, s[26:27]
	s_add_i32 m0, s84, 0x2000
	s_nop 0
	global_load_lds_dwordx4 v132, s[26:27]
	s_waitcnt vmcnt(10)
	s_barrier
	s_waitcnt lgkmcnt(0)
	v_mfma_f32_16x16x32_bf16 v[46:49], v[204:207], v[224:227], v[46:49]
	ds_read_b128 v[152:155], v149
	v_mfma_f32_16x16x32_bf16 v[42:45], v[212:215], v[224:227], v[42:45]
	v_mfma_f32_16x16x32_bf16 v[30:33], v[204:207], v[232:235], v[30:33]
	v_mfma_f32_16x16x32_bf16 v[26:29], v[212:215], v[232:235], v[26:29]
	v_mfma_f32_16x16x32_bf16 v[14:17], v[204:207], v[240:243], v[14:17]
	ds_read_b128 v[156:159], v149 offset:1024
	v_mfma_f32_16x16x32_bf16 v[10:13], v[212:215], v[240:243], v[10:13]
	v_mfma_f32_16x16x32_bf16 v[6:9], v[204:207], v[248:251], v[6:9]
	v_mfma_f32_16x16x32_bf16 v[2:5], v[212:215], v[248:251], v[2:5]
	v_mfma_f32_16x16x32_bf16 v[46:49], v[208:211], v[228:231], v[46:49]
	ds_read_b128 v[160:163], v149 offset:2048
	v_mfma_f32_16x16x32_bf16 v[42:45], v[216:219], v[228:231], v[42:45]
	v_mfma_f32_16x16x32_bf16 v[30:33], v[208:211], v[236:239], v[30:33]
	v_mfma_f32_16x16x32_bf16 v[26:29], v[216:219], v[236:239], v[26:29]
	v_mfma_f32_16x16x32_bf16 v[14:17], v[208:211], v[244:247], v[14:17]
	ds_read_b128 v[168:171], v149 offset:3072
	v_mfma_f32_16x16x32_bf16 v[10:13], v[216:219], v[244:247], v[10:13]
	v_mfma_f32_16x16x32_bf16 v[6:9], v[208:211], v[164:167], v[6:9]
	v_mfma_f32_16x16x32_bf16 v[2:5], v[216:219], v[164:167], v[2:5]
	s_add_i32 s54, s54, 2
	s_add_u32 s24, s24, 0x100
	s_addc_u32 s25, s25, 0
	s_add_u32 s52, s52, 0x100
	s_addc_u32 s53, s53, 0
	s_cmp_gt_u32 s54, 29
	s_barrier
	s_cbranch_scc0 .LBB0_377

.LBB0_384:
	s_setprio 0
	s_waitcnt vmcnt(0)
	s_cmpk_gt_u32 s30, 0xff
	s_cbranch_scc1 .LBB0_386
	s_barrier

.LBB0_937:
	s_lshl_b32 s14, s14, 5
	s_and_b32 s19, s14, 0x60
	s_mov_b64 s[14:15], 0x80
	s_add_i32 m0, s37, 0x18000
	v_lshl_add_u64 v[2:3], v[2:3], 0, s[14:15]
	s_lshl_b32 s18, s5, 13
	s_waitcnt vmcnt(4)
	s_barrier
	global_load_lds_dwordx4 v[2:3], off
	v_lshl_add_u64 v[2:3], v[4:5], 0, s[14:15]
	s_add_i32 m0, s37, 0x1a000
	s_add_i32 s57, s37, 0x8000
	s_add_i32 s58, s37, 0xa000
	global_load_lds_dwordx4 v[2:3], off
	v_lshl_add_u64 v[2:3], v[8:9], 0, s[14:15]
	s_mov_b32 m0, s57
	s_add_u32 s16, s40, 0x80080
	global_load_lds_dwordx4 v[2:3], off
	v_lshl_add_u64 v[2:3], v[6:7], 0, s[14:15]
	s_mov_b32 m0, s58
	s_addc_u32 s17, s41, 0
	global_load_lds_dwordx4 v[2:3], off
	s_add_i32 m0, s37, 0x1c000
	v_lshl_add_u64 v[2:3], s[16:17], 0, v[146:147]
	global_load_lds_dwordx4 v[2:3], off
	v_lshl_add_u64 v[2:3], s[16:17], 0, v[148:149]
	s_add_i32 m0, s37, 0x1e000
	v_and_b32_e32 v4, 15, v0
	global_load_lds_dwordx4 v[2:3], off
	v_lshlrev_b32_e32 v3, 2, v4
	v_lshl_or_b32 v2, v4, 6, v1
	v_and_b32_e32 v3, 32, v3
	v_bitop3_b32 v2, v2, s18, v3 bitop3:0xde
	v_lshlrev_b32_e32 v3, 9, v162
	v_lshl_or_b32 v163, s5, 6, v4
	v_and_b32_e32 v3, 0x70000, v3
	v_lshlrev_b32_e32 v4, 12, v12
	v_or3_b32 v3, v10, v3, v4
	v_add_u32_e32 v150, v3, v11
	v_lshlrev_b32_e32 v3, 5, v13
	s_waitcnt vmcnt(6)
	v_and_b32_e32 v3, 0x70000, v3
	v_lshl_or_b32 v164, s19, 7, v161
	v_mov_b32_e32 v151, 0
	v_or3_b32 v3, v10, v3, v4
	s_add_i32 s59, 0, 0x10000
	s_add_i32 s60, 0, 0x14000
	s_sext_i32_i8 s62, s4
	v_or_b32_e32 v165, s19, v254
	v_add_u32_e32 v152, v3, v11
	v_mov_b32_e32 v153, v151
	v_mov_b64_e32 v[154:155], 0x200
	v_mov_b64_e32 v[156:157], 0x1ff
	v_add_u32_e32 v167, s59, v164
	v_add_u32_e32 v170, 0, v2
	v_add_u32_e32 v171, s60, v164
	s_mov_b64 s[16:17], 0x6104000
	s_mov_b32 s61, 0x6104000
	s_mov_b64 s[18:19], 0x100000
	s_mov_b64 s[20:21], 0x120000
	s_mov_b64 s[22:23], 0x140000
	s_mov_b64 s[24:25], 0x160000
	s_barrier
	s_cmpk_lt_u32 s47, 0x1000
	s_cbranch_scc0 .Lp6_prio_done
	s_setprio 1
.Lp6_prio_done:
.LBB0_938:
	s_add_i32 s53, s53, 1
	s_mul_i32 s4, s53, s56
	s_mul_hi_u32 s5, s53, s33
	s_add_i32 s5, s5, s4
	s_mul_i32 s4, s53, s33
	s_add_u32 s30, s4, s44
	s_addc_u32 s31, s5, s46
	v_cmp_gt_i64_e64 s[4:5], s[30:31], v[156:157]
	s_and_b64 vcc, exec, s[4:5]
	s_cbranch_vccnz .LBB0_944
	s_ashr_i32 s26, s30, 31
	s_lshr_b32 s26, s26, 29
	s_add_i32 s28, s30, s26
	s_and_b32 s26, s28, -8
	s_sub_i32 s29, s30, s26
	s_cmp_gt_i32 s29, -1
	s_mov_b64 s[26:27], -1
	s_cbranch_scc0 .LBB0_941
	s_lshl_b32 s34, s29, 6
	s_mov_b64 s[26:27], 0

.LBB0_944:
	v_add_u32_e32 v158, 0x18000, v164
	v_add_u32_e32 v159, 0x1c000, v164
	ds_read_b128 v[130:133], v167
	ds_read_b128 v[134:137], v167 offset:1024
	ds_read_b128 v[138:141], v167 offset:2048
	ds_read_b128 v[142:145], v167 offset:3072
	ds_read_b128 v[172:175], v170
	ds_read_b128 v[176:179], v170 offset:1024
	ds_read_b128 v[180:183], v170 offset:2048
	ds_read_b128 v[184:187], v170 offset:3072
	ds_read_b128 v[188:191], v170 offset:4096
	ds_read_b128 v[192:195], v170 offset:5120
	ds_read_b128 v[196:199], v170 offset:6144
	ds_read_b128 v[200:203], v170 offset:7168
	s_ashr_i32 s29, s28, 31
	v_cmp_lt_i64_e32 vcc, s[30:31], v[154:155]
	s_lshl_b64 s[30:31], s[28:29], 20
	s_add_u32 s30, s48, s30
	s_addc_u32 s31, s49, s31
	s_and_b64 s[34:35], vcc, exec
	s_cselect_b32 s29, s31, s39
	s_cselect_b32 s63, s30, s38
	s_ashr_i32 s27, s26, 31
	s_lshl_b64 s[34:35], s[26:27], 20
	s_add_u32 s34, s54, s34
	s_addc_u32 s35, s55, s35
	s_and_b64 s[42:43], vcc, exec
	s_cselect_b32 s27, s35, s41
	s_cselect_b32 s64, s34, s40
	s_add_u32 s38, s38, 0x80080
	s_addc_u32 s39, s39, 0
	s_add_u32 s65, s40, 0x100
	s_addc_u32 s66, s41, 0
	s_mov_b32 s67, -2
	s_add_u32 s40, s38, 0xfff80080
	s_addc_u32 s41, s39, -1
	s_cmp_eq_u32 s67, 28
	s_cselect_b32 s43, s29, s41
	s_cselect_b32 s42, s63, s40
	s_cselect_b32 s41, s27, s66
	s_cselect_b32 s40, s64, s65
	s_add_i32 m0, s37, 0xc000
	s_nop 0
	global_load_lds_dwordx4 v150, s[38:39]
	s_add_i32 m0, s37, 0xe000
	s_nop 0
	global_load_lds_dwordx4 v152, s[38:39]
	s_waitcnt vmcnt(10)
	s_barrier
	s_waitcnt lgkmcnt(0)
	v_mfma_f32_16x16x32_bf16 v[126:129], v[130:133], v[172:175], 0
	ds_read_b128 v[204:207], v171
	v_mfma_f32_16x16x32_bf16 v[122:125], v[138:141], v[172:175], 0
	v_mfma_f32_16x16x32_bf16 v[114:117], v[130:133], v[180:183], 0
	v_mfma_f32_16x16x32_bf16 v[106:109], v[138:141], v[180:183], 0
	v_mfma_f32_16x16x32_bf16 v[98:101], v[130:133], v[188:191], 0
	ds_read_b128 v[208:211], v171 offset:1024
	v_mfma_f32_16x16x32_bf16 v[90:93], v[138:141], v[188:191], 0
	v_mfma_f32_16x16x32_bf16 v[82:85], v[130:133], v[196:199], 0
	v_mfma_f32_16x16x32_bf16 v[74:77], v[138:141], v[196:199], 0
	v_mfma_f32_16x16x32_bf16 v[126:129], v[134:137], v[176:179], v[126:129]
	ds_read_b128 v[212:215], v171 offset:2048
	v_mfma_f32_16x16x32_bf16 v[122:125], v[142:145], v[176:179], v[122:125]
	v_mfma_f32_16x16x32_bf16 v[114:117], v[134:137], v[184:187], v[114:117]
	v_mfma_f32_16x16x32_bf16 v[106:109], v[142:145], v[184:187], v[106:109]
	v_mfma_f32_16x16x32_bf16 v[98:101], v[134:137], v[192:195], v[98:101]
	ds_read_b128 v[216:219], v171 offset:3072
	v_mfma_f32_16x16x32_bf16 v[90:93], v[142:145], v[192:195], v[90:93]
	v_mfma_f32_16x16x32_bf16 v[82:85], v[134:137], v[200:203], v[82:85]
	v_mfma_f32_16x16x32_bf16 v[74:77], v[142:145], v[200:203], v[74:77]
	s_barrier
	s_add_i32 s68, s59, s47
	s_add_u32 s96, s40, 0x80
	s_addc_u32 s97, s41, 0
	s_mov_b32 m0, s68
	s_nop 0
	global_load_lds_dwordx4 v146, s[40:41]
	s_add_i32 m0, s68, 0x2000
	s_nop 0
	global_load_lds_dwordx4 v148, s[40:41]
	s_waitcnt vmcnt(10)
	s_barrier
	s_waitcnt lgkmcnt(0)
	v_mfma_f32_16x16x32_bf16 v[118:121], v[204:207], v[172:175], 0
	ds_read_b128 v[224:227], v170 offset:16384
	v_mfma_f32_16x16x32_bf16 v[110:113], v[212:215], v[172:175], 0
	v_mfma_f32_16x16x32_bf16 v[102:105], v[204:207], v[180:183], 0
	ds_read_b128 v[228:231], v170 offset:17408
	v_mfma_f32_16x16x32_bf16 v[94:97], v[212:215], v[180:183], 0
	v_mfma_f32_16x16x32_bf16 v[86:89], v[204:207], v[188:191], 0
	ds_read_b128 v[232:235], v170 offset:18432
	v_mfma_f32_16x16x32_bf16 v[78:81], v[212:215], v[188:191], 0
	v_mfma_f32_16x16x32_bf16 v[70:73], v[204:207], v[196:199], 0
	ds_read_b128 v[236:239], v170 offset:19456
	v_mfma_f32_16x16x32_bf16 v[66:69], v[212:215], v[196:199], 0
	v_mfma_f32_16x16x32_bf16 v[118:121], v[208:211], v[176:179], v[118:121]
	ds_read_b128 v[240:243], v170 offset:20480
	v_mfma_f32_16x16x32_bf16 v[110:113], v[216:219], v[176:179], v[110:113]
	v_mfma_f32_16x16x32_bf16 v[102:105], v[208:211], v[184:187], v[102:105]
	ds_read_b128 v[244:247], v170 offset:21504
	v_mfma_f32_16x16x32_bf16 v[94:97], v[216:219], v[184:187], v[94:97]
	v_mfma_f32_16x16x32_bf16 v[86:89], v[208:211], v[192:195], v[86:89]
	ds_read_b128 v[248:251], v170 offset:22528
	v_mfma_f32_16x16x32_bf16 v[78:81], v[216:219], v[192:195], v[78:81]
	v_mfma_f32_16x16x32_bf16 v[70:73], v[208:211], v[200:203], v[70:73]
	ds_read_b128 v[220:223], v170 offset:23552
	v_mfma_f32_16x16x32_bf16 v[66:69], v[216:219], v[200:203], v[66:69]
	s_barrier
	s_mov_b32 m0, s37
	s_add_u32 s94, s42, 0x80
	s_addc_u32 s95, s43, 0
	global_load_lds_dwordx4 v146, s[42:43]
	s_mov_b32 m0, s50
	s_nop 0
	global_load_lds_dwordx4 v148, s[42:43]
	s_waitcnt vmcnt(8)
	s_barrier
	s_waitcnt lgkmcnt(0)
	v_mfma_f32_16x16x32_bf16 v[62:65], v[130:133], v[224:227], 0
	ds_read_b128 v[172:175], v170 offset:32768
	v_mfma_f32_16x16x32_bf16 v[58:61], v[138:141], v[224:227], 0
	v_mfma_f32_16x16x32_bf16 v[54:57], v[130:133], v[232:235], 0
	ds_read_b128 v[176:179], v170 offset:33792
	v_mfma_f32_16x16x32_bf16 v[46:49], v[138:141], v[232:235], 0
	v_mfma_f32_16x16x32_bf16 v[38:41], v[130:133], v[240:243], 0
	ds_read_b128 v[180:183], v170 offset:34816
	v_mfma_f32_16x16x32_bf16 v[30:33], v[138:141], v[240:243], 0
	v_mfma_f32_16x16x32_bf16 v[22:25], v[130:133], v[248:251], 0
	ds_read_b128 v[184:187], v170 offset:35840
	v_mfma_f32_16x16x32_bf16 v[14:17], v[138:141], v[248:251], 0
	v_mfma_f32_16x16x32_bf16 v[62:65], v[134:137], v[228:231], v[62:65]
	ds_read_b128 v[188:191], v170 offset:36864
	v_mfma_f32_16x16x32_bf16 v[58:61], v[142:145], v[228:231], v[58:61]
	v_mfma_f32_16x16x32_bf16 v[54:57], v[134:137], v[236:239], v[54:57]
	ds_read_b128 v[192:195], v170 offset:37888
	v_mfma_f32_16x16x32_bf16 v[46:49], v[142:145], v[236:239], v[46:49]
	v_mfma_f32_16x16x32_bf16 v[38:41], v[134:137], v[244:247], v[38:41]
	ds_read_b128 v[196:199], v170 offset:38912
	v_mfma_f32_16x16x32_bf16 v[30:33], v[142:145], v[244:247], v[30:33]
	v_mfma_f32_16x16x32_bf16 v[22:25], v[134:137], v[220:223], v[22:25]
	ds_read_b128 v[200:203], v170 offset:39936
	v_mfma_f32_16x16x32_bf16 v[14:17], v[142:145], v[220:223], v[14:17]
	s_barrier
	s_add_u32 s68, s40, 0x80000
	s_addc_u32 s69, s41, 0
	s_add_i32 s70, s60, s47
	s_mov_b32 m0, s70
	s_nop 0
	global_load_lds_dwordx4 v146, s[68:69]
	s_add_i32 m0, s70, 0x2000
	s_nop 0
	global_load_lds_dwordx4 v148, s[68:69]
	s_waitcnt vmcnt(10)
	s_barrier
	s_waitcnt lgkmcnt(0)
	v_mfma_f32_16x16x32_bf16 v[50:53], v[204:207], v[224:227], 0
	ds_read_b128 v[130:133], v158
	v_mfma_f32_16x16x32_bf16 v[42:45], v[212:215], v[224:227], 0
	v_mfma_f32_16x16x32_bf16 v[34:37], v[204:207], v[232:235], 0
	v_mfma_f32_16x16x32_bf16 v[26:29], v[212:215], v[232:235], 0
	v_mfma_f32_16x16x32_bf16 v[18:21], v[204:207], v[240:243], 0
	ds_read_b128 v[134:137], v158 offset:1024
	v_mfma_f32_16x16x32_bf16 v[10:13], v[212:215], v[240:243], 0
	v_mfma_f32_16x16x32_bf16 v[6:9], v[204:207], v[248:251], 0
	v_mfma_f32_16x16x32_bf16 v[2:5], v[212:215], v[248:251], 0
	v_mfma_f32_16x16x32_bf16 v[50:53], v[208:211], v[228:231], v[50:53]
	ds_read_b128 v[138:141], v158 offset:2048
	v_mfma_f32_16x16x32_bf16 v[42:45], v[216:219], v[228:231], v[42:45]
	v_mfma_f32_16x16x32_bf16 v[34:37], v[208:211], v[236:239], v[34:37]
	v_mfma_f32_16x16x32_bf16 v[26:29], v[216:219], v[236:239], v[26:29]
	v_mfma_f32_16x16x32_bf16 v[18:21], v[208:211], v[244:247], v[18:21]
	ds_read_b128 v[142:145], v158 offset:3072
	v_mfma_f32_16x16x32_bf16 v[10:13], v[216:219], v[244:247], v[10:13]
	v_mfma_f32_16x16x32_bf16 v[6:9], v[208:211], v[220:223], v[6:9]
	v_mfma_f32_16x16x32_bf16 v[2:5], v[216:219], v[220:223], v[2:5]
	s_barrier
	s_add_i32 s70, 0, 0x18000
	s_add_u32 s42, s42, 0x80000
	s_addc_u32 s43, s43, 0
	s_mov_b32 m0, s51
	s_nop 0
	global_load_lds_dwordx4 v146, s[42:43]
	s_mov_b32 m0, s52
	s_nop 0
	global_load_lds_dwordx4 v148, s[42:43]
	s_waitcnt vmcnt(10)
	s_barrier
	s_waitcnt lgkmcnt(0)
	v_mfma_f32_16x16x32_bf16 v[126:129], v[130:133], v[172:175], v[126:129]
	ds_read_b128 v[204:207], v159
	v_mfma_f32_16x16x32_bf16 v[122:125], v[138:141], v[172:175], v[122:125]
	v_mfma_f32_16x16x32_bf16 v[114:117], v[130:133], v[180:183], v[114:117]
	v_mfma_f32_16x16x32_bf16 v[106:109], v[138:141], v[180:183], v[106:109]
	v_mfma_f32_16x16x32_bf16 v[98:101], v[130:133], v[188:191], v[98:101]
	ds_read_b128 v[208:211], v159 offset:1024
	v_mfma_f32_16x16x32_bf16 v[90:93], v[138:141], v[188:191], v[90:93]
	v_mfma_f32_16x16x32_bf16 v[82:85], v[130:133], v[196:199], v[82:85]
	v_mfma_f32_16x16x32_bf16 v[74:77], v[138:141], v[196:199], v[74:77]
	v_mfma_f32_16x16x32_bf16 v[126:129], v[134:137], v[176:179], v[126:129]
	ds_read_b128 v[212:215], v159 offset:2048
	v_mfma_f32_16x16x32_bf16 v[122:125], v[142:145], v[176:179], v[122:125]
	v_mfma_f32_16x16x32_bf16 v[114:117], v[134:137], v[184:187], v[114:117]
	v_mfma_f32_16x16x32_bf16 v[106:109], v[142:145], v[184:187], v[106:109]
	v_mfma_f32_16x16x32_bf16 v[98:101], v[134:137], v[192:195], v[98:101]
	ds_read_b128 v[216:219], v159 offset:3072
	v_mfma_f32_16x16x32_bf16 v[90:93], v[142:145], v[192:195], v[90:93]
	v_mfma_f32_16x16x32_bf16 v[82:85], v[134:137], v[200:203], v[82:85]
	v_mfma_f32_16x16x32_bf16 v[74:77], v[142:145], v[200:203], v[74:77]
	s_barrier
	s_add_i32 s84, 0, 0x1c000
	s_add_i32 s85, s70, s47
	s_mov_b32 m0, s85
	s_nop 0
	global_load_lds_dwordx4 v146, s[96:97]
	s_add_i32 m0, s85, 0x2000
	s_nop 0
	global_load_lds_dwordx4 v148, s[96:97]
	s_waitcnt vmcnt(10)
	s_barrier
	s_waitcnt lgkmcnt(0)
	v_mfma_f32_16x16x32_bf16 v[118:121], v[204:207], v[172:175], v[118:121]
	ds_read_b128 v[224:227], v170 offset:49152
	v_mfma_f32_16x16x32_bf16 v[110:113], v[212:215], v[172:175], v[110:113]
	v_mfma_f32_16x16x32_bf16 v[102:105], v[204:207], v[180:183], v[102:105]
	ds_read_b128 v[228:231], v170 offset:50176
	v_mfma_f32_16x16x32_bf16 v[94:97], v[212:215], v[180:183], v[94:97]
	v_mfma_f32_16x16x32_bf16 v[86:89], v[204:207], v[188:191], v[86:89]
	ds_read_b128 v[232:235], v170 offset:51200
	v_mfma_f32_16x16x32_bf16 v[78:81], v[212:215], v[188:191], v[78:81]
	v_mfma_f32_16x16x32_bf16 v[70:73], v[204:207], v[196:199], v[70:73]
	ds_read_b128 v[236:239], v170 offset:52224
	v_mfma_f32_16x16x32_bf16 v[66:69], v[212:215], v[196:199], v[66:69]
	v_mfma_f32_16x16x32_bf16 v[118:121], v[208:211], v[176:179], v[118:121]
	ds_read_b128 v[240:243], v170 offset:53248
	v_mfma_f32_16x16x32_bf16 v[110:113], v[216:219], v[176:179], v[110:113]
	v_mfma_f32_16x16x32_bf16 v[102:105], v[208:211], v[184:187], v[102:105]
	ds_read_b128 v[244:247], v170 offset:54272
	v_mfma_f32_16x16x32_bf16 v[94:97], v[216:219], v[184:187], v[94:97]
	v_mfma_f32_16x16x32_bf16 v[86:89], v[208:211], v[192:195], v[86:89]
	ds_read_b128 v[248:251], v170 offset:55296
	v_mfma_f32_16x16x32_bf16 v[78:81], v[216:219], v[192:195], v[78:81]
	v_mfma_f32_16x16x32_bf16 v[70:73], v[208:211], v[200:203], v[70:73]
	ds_read_b128 v[220:223], v170 offset:56320
	v_mfma_f32_16x16x32_bf16 v[66:69], v[216:219], v[200:203], v[66:69]
	s_barrier
	s_mov_b32 m0, s57
	s_nop 0
	global_load_lds_dwordx4 v146, s[94:95]
	s_mov_b32 m0, s58
	s_nop 0
	global_load_lds_dwordx4 v148, s[94:95]
	s_waitcnt vmcnt(8)
	s_barrier
	s_waitcnt lgkmcnt(0)
	v_mfma_f32_16x16x32_bf16 v[62:65], v[130:133], v[224:227], v[62:65]
	ds_read_b128 v[172:175], v170
	v_mfma_f32_16x16x32_bf16 v[58:61], v[138:141], v[224:227], v[58:61]
	v_mfma_f32_16x16x32_bf16 v[54:57], v[130:133], v[232:235], v[54:57]
	ds_read_b128 v[176:179], v170 offset:1024
	v_mfma_f32_16x16x32_bf16 v[46:49], v[138:141], v[232:235], v[46:49]
	v_mfma_f32_16x16x32_bf16 v[38:41], v[130:133], v[240:243], v[38:41]
	ds_read_b128 v[180:183], v170 offset:2048
	v_mfma_f32_16x16x32_bf16 v[30:33], v[138:141], v[240:243], v[30:33]
	v_mfma_f32_16x16x32_bf16 v[22:25], v[130:133], v[248:251], v[22:25]
	ds_read_b128 v[184:187], v170 offset:3072
	v_mfma_f32_16x16x32_bf16 v[14:17], v[138:141], v[248:251], v[14:17]
	v_mfma_f32_16x16x32_bf16 v[62:65], v[134:137], v[228:231], v[62:65]
	ds_read_b128 v[188:191], v170 offset:4096
	v_mfma_f32_16x16x32_bf16 v[58:61], v[142:145], v[228:231], v[58:61]
	v_mfma_f32_16x16x32_bf16 v[54:57], v[134:137], v[236:239], v[54:57]
	ds_read_b128 v[192:195], v170 offset:5120
	v_mfma_f32_16x16x32_bf16 v[46:49], v[142:145], v[236:239], v[46:49]
	v_mfma_f32_16x16x32_bf16 v[38:41], v[134:137], v[244:247], v[38:41]
	ds_read_b128 v[196:199], v170 offset:6144
	v_mfma_f32_16x16x32_bf16 v[30:33], v[142:145], v[244:247], v[30:33]
	v_mfma_f32_16x16x32_bf16 v[22:25], v[134:137], v[220:223], v[22:25]
	ds_read_b128 v[200:203], v170 offset:7168
	v_mfma_f32_16x16x32_bf16 v[14:17], v[142:145], v[220:223], v[14:17]
	s_barrier
	s_add_u32 s40, s40, 0x80080
	s_addc_u32 s41, s41, 0
	s_add_i32 s84, s84, s47
	s_mov_b32 m0, s84
	s_nop 0
	global_load_lds_dwordx4 v146, s[40:41]
	s_add_i32 m0, s84, 0x2000
	s_nop 0
	global_load_lds_dwordx4 v148, s[40:41]
	s_waitcnt vmcnt(10)
	s_barrier
	s_waitcnt lgkmcnt(0)
	v_mfma_f32_16x16x32_bf16 v[50:53], v[204:207], v[224:227], v[50:53]
	ds_read_b128 v[130:133], v167
	v_mfma_f32_16x16x32_bf16 v[42:45], v[212:215], v[224:227], v[42:45]
	v_mfma_f32_16x16x32_bf16 v[34:37], v[204:207], v[232:235], v[34:37]
	v_mfma_f32_16x16x32_bf16 v[26:29], v[212:215], v[232:235], v[26:29]
	v_mfma_f32_16x16x32_bf16 v[18:21], v[204:207], v[240:243], v[18:21]
	ds_read_b128 v[134:137], v167 offset:1024
	v_mfma_f32_16x16x32_bf16 v[10:13], v[212:215], v[240:243], v[10:13]
	v_mfma_f32_16x16x32_bf16 v[6:9], v[204:207], v[248:251], v[6:9]
	v_mfma_f32_16x16x32_bf16 v[2:5], v[212:215], v[248:251], v[2:5]
	v_mfma_f32_16x16x32_bf16 v[50:53], v[208:211], v[228:231], v[50:53]
	ds_read_b128 v[138:141], v167 offset:2048
	v_mfma_f32_16x16x32_bf16 v[42:45], v[216:219], v[228:231], v[42:45]
	v_mfma_f32_16x16x32_bf16 v[34:37], v[208:211], v[236:239], v[34:37]
	v_mfma_f32_16x16x32_bf16 v[26:29], v[216:219], v[236:239], v[26:29]
	v_mfma_f32_16x16x32_bf16 v[18:21], v[208:211], v[244:247], v[18:21]
	ds_read_b128 v[142:145], v167 offset:3072
	v_mfma_f32_16x16x32_bf16 v[10:13], v[216:219], v[244:247], v[10:13]
	v_mfma_f32_16x16x32_bf16 v[6:9], v[208:211], v[220:223], v[6:9]
	v_mfma_f32_16x16x32_bf16 v[2:5], v[216:219], v[220:223], v[2:5]
	s_add_i32 s67, s67, 2
	s_add_u32 s38, s38, 0x100
	s_addc_u32 s39, s39, 0
	s_add_u32 s65, s65, 0x100
	s_addc_u32 s66, s66, 0
	s_cmp_gt_u32 s67, 29
	s_barrier
	s_cbranch_scc0 .LBB0_945
	s_branch .Lp6_loop_exit
.LBB0_945:
	s_add_u32 s40, s38, 0xfff80080
	s_addc_u32 s41, s39, -1
	s_cmp_eq_u32 s67, 28
	s_cselect_b32 s43, s29, s41
	s_cselect_b32 s42, s63, s40
	s_cselect_b32 s41, s27, s66
	s_cselect_b32 s40, s64, s65
	s_add_i32 m0, s37, 0xc000
	s_nop 0
	global_load_lds_dwordx4 v150, s[38:39]
	s_add_i32 m0, s37, 0xe000
	s_nop 0
	global_load_lds_dwordx4 v152, s[38:39]
	s_waitcnt vmcnt(10)
	s_barrier
	s_waitcnt lgkmcnt(0)
	v_mfma_f32_16x16x32_bf16 v[126:129], v[130:133], v[172:175], v[126:129]
	ds_read_b128 v[204:207], v171
	v_mfma_f32_16x16x32_bf16 v[122:125], v[138:141], v[172:175], v[122:125]
	v_mfma_f32_16x16x32_bf16 v[114:117], v[130:133], v[180:183], v[114:117]
	v_mfma_f32_16x16x32_bf16 v[106:109], v[138:141], v[180:183], v[106:109]
	v_mfma_f32_16x16x32_bf16 v[98:101], v[130:133], v[188:191], v[98:101]
	ds_read_b128 v[208:211], v171 offset:1024
	v_mfma_f32_16x16x32_bf16 v[90:93], v[138:141], v[188:191], v[90:93]
	v_mfma_f32_16x16x32_bf16 v[82:85], v[130:133], v[196:199], v[82:85]
	v_mfma_f32_16x16x32_bf16 v[74:77], v[138:141], v[196:199], v[74:77]
	v_mfma_f32_16x16x32_bf16 v[126:129], v[134:137], v[176:179], v[126:129]
	ds_read_b128 v[212:215], v171 offset:2048
	v_mfma_f32_16x16x32_bf16 v[122:125], v[142:145], v[176:179], v[122:125]
	v_mfma_f32_16x16x32_bf16 v[114:117], v[134:137], v[184:187], v[114:117]
	v_mfma_f32_16x16x32_bf16 v[106:109], v[142:145], v[184:187], v[106:109]
	v_mfma_f32_16x16x32_bf16 v[98:101], v[134:137], v[192:195], v[98:101]
	ds_read_b128 v[216:219], v171 offset:3072
	v_mfma_f32_16x16x32_bf16 v[90:93], v[142:145], v[192:195], v[90:93]
	v_mfma_f32_16x16x32_bf16 v[82:85], v[134:137], v[200:203], v[82:85]
	v_mfma_f32_16x16x32_bf16 v[74:77], v[142:145], v[200:203], v[74:77]
	s_barrier
	s_add_i32 s68, s59, s47
	s_add_u32 s96, s40, 0x80
	s_addc_u32 s97, s41, 0
	s_mov_b32 m0, s68
	s_nop 0
	global_load_lds_dwordx4 v146, s[40:41]
	s_add_i32 m0, s68, 0x2000
	s_nop 0
	global_load_lds_dwordx4 v148, s[40:41]
	s_waitcnt vmcnt(10)
	s_barrier
	s_waitcnt lgkmcnt(0)
	v_mfma_f32_16x16x32_bf16 v[118:121], v[204:207], v[172:175], v[118:121]
	ds_read_b128 v[224:227], v170 offset:16384
	v_mfma_f32_16x16x32_bf16 v[110:113], v[212:215], v[172:175], v[110:113]
	v_mfma_f32_16x16x32_bf16 v[102:105], v[204:207], v[180:183], v[102:105]
	ds_read_b128 v[228:231], v170 offset:17408
	v_mfma_f32_16x16x32_bf16 v[94:97], v[212:215], v[180:183], v[94:97]
	v_mfma_f32_16x16x32_bf16 v[86:89], v[204:207], v[188:191], v[86:89]
	ds_read_b128 v[232:235], v170 offset:18432
	v_mfma_f32_16x16x32_bf16 v[78:81], v[212:215], v[188:191], v[78:81]
	v_mfma_f32_16x16x32_bf16 v[70:73], v[204:207], v[196:199], v[70:73]
	ds_read_b128 v[236:239], v170 offset:19456
	v_mfma_f32_16x16x32_bf16 v[66:69], v[212:215], v[196:199], v[66:69]
	v_mfma_f32_16x16x32_bf16 v[118:121], v[208:211], v[176:179], v[118:121]
	ds_read_b128 v[240:243], v170 offset:20480
	v_mfma_f32_16x16x32_bf16 v[110:113], v[216:219], v[176:179], v[110:113]
	v_mfma_f32_16x16x32_bf16 v[102:105], v[208:211], v[184:187], v[102:105]
	ds_read_b128 v[244:247], v170 offset:21504
	v_mfma_f32_16x16x32_bf16 v[94:97], v[216:219], v[184:187], v[94:97]
	v_mfma_f32_16x16x32_bf16 v[86:89], v[208:211], v[192:195], v[86:89]
	ds_read_b128 v[248:251], v170 offset:22528
	v_mfma_f32_16x16x32_bf16 v[78:81], v[216:219], v[192:195], v[78:81]
	v_mfma_f32_16x16x32_bf16 v[70:73], v[208:211], v[200:203], v[70:73]
	ds_read_b128 v[220:223], v170 offset:23552
	v_mfma_f32_16x16x32_bf16 v[66:69], v[216:219], v[200:203], v[66:69]
	s_barrier
	s_mov_b32 m0, s37
	s_add_u32 s94, s42, 0x80
	s_addc_u32 s95, s43, 0
	global_load_lds_dwordx4 v146, s[42:43]
	s_mov_b32 m0, s50
	s_nop 0
	global_load_lds_dwordx4 v148, s[42:43]
	s_waitcnt vmcnt(8)
	s_barrier
	s_waitcnt lgkmcnt(0)
	v_mfma_f32_16x16x32_bf16 v[62:65], v[130:133], v[224:227], v[62:65]
	ds_read_b128 v[172:175], v170 offset:32768
	v_mfma_f32_16x16x32_bf16 v[58:61], v[138:141], v[224:227], v[58:61]
	v_mfma_f32_16x16x32_bf16 v[54:57], v[130:133], v[232:235], v[54:57]
	ds_read_b128 v[176:179], v170 offset:33792
	v_mfma_f32_16x16x32_bf16 v[46:49], v[138:141], v[232:235], v[46:49]
	v_mfma_f32_16x16x32_bf16 v[38:41], v[130:133], v[240:243], v[38:41]
	ds_read_b128 v[180:183], v170 offset:34816
	v_mfma_f32_16x16x32_bf16 v[30:33], v[138:141], v[240:243], v[30:33]
	v_mfma_f32_16x16x32_bf16 v[22:25], v[130:133], v[248:251], v[22:25]
	ds_read_b128 v[184:187], v170 offset:35840
	v_mfma_f32_16x16x32_bf16 v[14:17], v[138:141], v[248:251], v[14:17]
	v_mfma_f32_16x16x32_bf16 v[62:65], v[134:137], v[228:231], v[62:65]
	ds_read_b128 v[188:191], v170 offset:36864
	v_mfma_f32_16x16x32_bf16 v[58:61], v[142:145], v[228:231], v[58:61]
	v_mfma_f32_16x16x32_bf16 v[54:57], v[134:137], v[236:239], v[54:57]
	ds_read_b128 v[192:195], v170 offset:37888
	v_mfma_f32_16x16x32_bf16 v[46:49], v[142:145], v[236:239], v[46:49]
	v_mfma_f32_16x16x32_bf16 v[38:41], v[134:137], v[244:247], v[38:41]
	ds_read_b128 v[196:199], v170 offset:38912
	v_mfma_f32_16x16x32_bf16 v[30:33], v[142:145], v[244:247], v[30:33]
	v_mfma_f32_16x16x32_bf16 v[22:25], v[134:137], v[220:223], v[22:25]
	ds_read_b128 v[200:203], v170 offset:39936
	v_mfma_f32_16x16x32_bf16 v[14:17], v[142:145], v[220:223], v[14:17]
	s_barrier
	s_add_u32 s68, s40, 0x80000
	s_addc_u32 s69, s41, 0
	s_add_i32 s70, s60, s47
	s_mov_b32 m0, s70
	s_nop 0
	global_load_lds_dwordx4 v146, s[68:69]
	s_add_i32 m0, s70, 0x2000
	s_nop 0
	global_load_lds_dwordx4 v148, s[68:69]
	s_waitcnt vmcnt(10)
	s_barrier
	s_waitcnt lgkmcnt(0)
	v_mfma_f32_16x16x32_bf16 v[50:53], v[204:207], v[224:227], v[50:53]
	ds_read_b128 v[130:133], v158
	v_mfma_f32_16x16x32_bf16 v[42:45], v[212:215], v[224:227], v[42:45]
	v_mfma_f32_16x16x32_bf16 v[34:37], v[204:207], v[232:235], v[34:37]
	v_mfma_f32_16x16x32_bf16 v[26:29], v[212:215], v[232:235], v[26:29]
	v_mfma_f32_16x16x32_bf16 v[18:21], v[204:207], v[240:243], v[18:21]
	ds_read_b128 v[134:137], v158 offset:1024
	v_mfma_f32_16x16x32_bf16 v[10:13], v[212:215], v[240:243], v[10:13]
	v_mfma_f32_16x16x32_bf16 v[6:9], v[204:207], v[248:251], v[6:9]
	v_mfma_f32_16x16x32_bf16 v[2:5], v[212:215], v[248:251], v[2:5]
	v_mfma_f32_16x16x32_bf16 v[50:53], v[208:211], v[228:231], v[50:53]
	ds_read_b128 v[138:141], v158 offset:2048
	v_mfma_f32_16x16x32_bf16 v[42:45], v[216:219], v[228:231], v[42:45]
	v_mfma_f32_16x16x32_bf16 v[34:37], v[208:211], v[236:239], v[34:37]
	v_mfma_f32_16x16x32_bf16 v[26:29], v[216:219], v[236:239], v[26:29]
	v_mfma_f32_16x16x32_bf16 v[18:21], v[208:211], v[244:247], v[18:21]
	ds_read_b128 v[142:145], v158 offset:3072
	v_mfma_f32_16x16x32_bf16 v[10:13], v[216:219], v[244:247], v[10:13]
	v_mfma_f32_16x16x32_bf16 v[6:9], v[208:211], v[220:223], v[6:9]
	v_mfma_f32_16x16x32_bf16 v[2:5], v[216:219], v[220:223], v[2:5]
	s_barrier
	s_add_i32 s70, 0, 0x18000
	s_add_u32 s42, s42, 0x80000
	s_addc_u32 s43, s43, 0
	s_mov_b32 m0, s51
	s_nop 0
	global_load_lds_dwordx4 v146, s[42:43]
	s_mov_b32 m0, s52
	s_nop 0
	global_load_lds_dwordx4 v148, s[42:43]
	s_waitcnt vmcnt(10)
	s_barrier
	s_waitcnt lgkmcnt(0)
	v_mfma_f32_16x16x32_bf16 v[126:129], v[130:133], v[172:175], v[126:129]
	ds_read_b128 v[204:207], v159
	v_mfma_f32_16x16x32_bf16 v[122:125], v[138:141], v[172:175], v[122:125]
	v_mfma_f32_16x16x32_bf16 v[114:117], v[130:133], v[180:183], v[114:117]
	v_mfma_f32_16x16x32_bf16 v[106:109], v[138:141], v[180:183], v[106:109]
	v_mfma_f32_16x16x32_bf16 v[98:101], v[130:133], v[188:191], v[98:101]
	ds_read_b128 v[208:211], v159 offset:1024
	v_mfma_f32_16x16x32_bf16 v[90:93], v[138:141], v[188:191], v[90:93]
	v_mfma_f32_16x16x32_bf16 v[82:85], v[130:133], v[196:199], v[82:85]
	v_mfma_f32_16x16x32_bf16 v[74:77], v[138:141], v[196:199], v[74:77]
	v_mfma_f32_16x16x32_bf16 v[126:129], v[134:137], v[176:179], v[126:129]
	ds_read_b128 v[212:215], v159 offset:2048
	v_mfma_f32_16x16x32_bf16 v[122:125], v[142:145], v[176:179], v[122:125]
	v_mfma_f32_16x16x32_bf16 v[114:117], v[134:137], v[184:187], v[114:117]
	v_mfma_f32_16x16x32_bf16 v[106:109], v[142:145], v[184:187], v[106:109]
	v_mfma_f32_16x16x32_bf16 v[98:101], v[134:137], v[192:195], v[98:101]
	ds_read_b128 v[216:219], v159 offset:3072
	v_mfma_f32_16x16x32_bf16 v[90:93], v[142:145], v[192:195], v[90:93]
	v_mfma_f32_16x16x32_bf16 v[82:85], v[134:137], v[200:203], v[82:85]
	v_mfma_f32_16x16x32_bf16 v[74:77], v[142:145], v[200:203], v[74:77]
	s_barrier
	s_add_i32 s84, 0, 0x1c000
	s_add_i32 s85, s70, s47
	s_mov_b32 m0, s85
	s_nop 0
	global_load_lds_dwordx4 v146, s[96:97]
	s_add_i32 m0, s85, 0x2000
	s_nop 0
	global_load_lds_dwordx4 v148, s[96:97]
	s_waitcnt vmcnt(10)
	s_barrier
	s_waitcnt lgkmcnt(0)
	v_mfma_f32_16x16x32_bf16 v[118:121], v[204:207], v[172:175], v[118:121]
	ds_read_b128 v[224:227], v170 offset:49152
	v_mfma_f32_16x16x32_bf16 v[110:113], v[212:215], v[172:175], v[110:113]
	v_mfma_f32_16x16x32_bf16 v[102:105], v[204:207], v[180:183], v[102:105]
	ds_read_b128 v[228:231], v170 offset:50176
	v_mfma_f32_16x16x32_bf16 v[94:97], v[212:215], v[180:183], v[94:97]
	v_mfma_f32_16x16x32_bf16 v[86:89], v[204:207], v[188:191], v[86:89]
	ds_read_b128 v[232:235], v170 offset:51200
	v_mfma_f32_16x16x32_bf16 v[78:81], v[212:215], v[188:191], v[78:81]
	v_mfma_f32_16x16x32_bf16 v[70:73], v[204:207], v[196:199], v[70:73]
	ds_read_b128 v[236:239], v170 offset:52224
	v_mfma_f32_16x16x32_bf16 v[66:69], v[212:215], v[196:199], v[66:69]
	v_mfma_f32_16x16x32_bf16 v[118:121], v[208:211], v[176:179], v[118:121]
	ds_read_b128 v[240:243], v170 offset:53248
	v_mfma_f32_16x16x32_bf16 v[110:113], v[216:219], v[176:179], v[110:113]
	v_mfma_f32_16x16x32_bf16 v[102:105], v[208:211], v[184:187], v[102:105]
	ds_read_b128 v[244:247], v170 offset:54272
	v_mfma_f32_16x16x32_bf16 v[94:97], v[216:219], v[184:187], v[94:97]
	v_mfma_f32_16x16x32_bf16 v[86:89], v[208:211], v[192:195], v[86:89]
	ds_read_b128 v[248:251], v170 offset:55296
	v_mfma_f32_16x16x32_bf16 v[78:81], v[216:219], v[192:195], v[78:81]
	v_mfma_f32_16x16x32_bf16 v[70:73], v[208:211], v[200:203], v[70:73]
	ds_read_b128 v[220:223], v170 offset:56320
	v_mfma_f32_16x16x32_bf16 v[66:69], v[216:219], v[200:203], v[66:69]
	s_barrier
	s_mov_b32 m0, s57
	s_nop 0
	global_load_lds_dwordx4 v146, s[94:95]
	s_mov_b32 m0, s58
	s_nop 0
	global_load_lds_dwordx4 v148, s[94:95]
	s_waitcnt vmcnt(8)
	s_barrier
	s_waitcnt lgkmcnt(0)
	v_mfma_f32_16x16x32_bf16 v[62:65], v[130:133], v[224:227], v[62:65]
	ds_read_b128 v[172:175], v170
	v_mfma_f32_16x16x32_bf16 v[58:61], v[138:141], v[224:227], v[58:61]
	v_mfma_f32_16x16x32_bf16 v[54:57], v[130:133], v[232:235], v[54:57]
	ds_read_b128 v[176:179], v170 offset:1024
	v_mfma_f32_16x16x32_bf16 v[46:49], v[138:141], v[232:235], v[46:49]
	v_mfma_f32_16x16x32_bf16 v[38:41], v[130:133], v[240:243], v[38:41]
	ds_read_b128 v[180:183], v170 offset:2048
	v_mfma_f32_16x16x32_bf16 v[30:33], v[138:141], v[240:243], v[30:33]
	v_mfma_f32_16x16x32_bf16 v[22:25], v[130:133], v[248:251], v[22:25]
	ds_read_b128 v[184:187], v170 offset:3072
	v_mfma_f32_16x16x32_bf16 v[14:17], v[138:141], v[248:251], v[14:17]
	v_mfma_f32_16x16x32_bf16 v[62:65], v[134:137], v[228:231], v[62:65]
	ds_read_b128 v[188:191], v170 offset:4096
	v_mfma_f32_16x16x32_bf16 v[58:61], v[142:145], v[228:231], v[58:61]
	v_mfma_f32_16x16x32_bf16 v[54:57], v[134:137], v[236:239], v[54:57]
	ds_read_b128 v[192:195], v170 offset:5120
	v_mfma_f32_16x16x32_bf16 v[46:49], v[142:145], v[236:239], v[46:49]
	v_mfma_f32_16x16x32_bf16 v[38:41], v[134:137], v[244:247], v[38:41]
	ds_read_b128 v[196:199], v170 offset:6144
	v_mfma_f32_16x16x32_bf16 v[30:33], v[142:145], v[244:247], v[30:33]
	v_mfma_f32_16x16x32_bf16 v[22:25], v[134:137], v[220:223], v[22:25]
	ds_read_b128 v[200:203], v170 offset:7168
	v_mfma_f32_16x16x32_bf16 v[14:17], v[142:145], v[220:223], v[14:17]
	s_barrier
	s_add_u32 s40, s40, 0x80080
	s_addc_u32 s41, s41, 0
	s_add_i32 s84, s84, s47
	s_mov_b32 m0, s84
	s_nop 0
	global_load_lds_dwordx4 v146, s[40:41]
	s_add_i32 m0, s84, 0x2000
	s_nop 0
	global_load_lds_dwordx4 v148, s[40:41]
	s_waitcnt vmcnt(10)
	s_barrier
	s_waitcnt lgkmcnt(0)
	v_mfma_f32_16x16x32_bf16 v[50:53], v[204:207], v[224:227], v[50:53]
	ds_read_b128 v[130:133], v167
	v_mfma_f32_16x16x32_bf16 v[42:45], v[212:215], v[224:227], v[42:45]
	v_mfma_f32_16x16x32_bf16 v[34:37], v[204:207], v[232:235], v[34:37]
	v_mfma_f32_16x16x32_bf16 v[26:29], v[212:215], v[232:235], v[26:29]
	v_mfma_f32_16x16x32_bf16 v[18:21], v[204:207], v[240:243], v[18:21]
	ds_read_b128 v[134:137], v167 offset:1024
	v_mfma_f32_16x16x32_bf16 v[10:13], v[212:215], v[240:243], v[10:13]
	v_mfma_f32_16x16x32_bf16 v[6:9], v[204:207], v[248:251], v[6:9]
	v_mfma_f32_16x16x32_bf16 v[2:5], v[212:215], v[248:251], v[2:5]
	v_mfma_f32_16x16x32_bf16 v[50:53], v[208:211], v[228:231], v[50:53]
	ds_read_b128 v[138:141], v167 offset:2048
	v_mfma_f32_16x16x32_bf16 v[42:45], v[216:219], v[228:231], v[42:45]
	v_mfma_f32_16x16x32_bf16 v[34:37], v[208:211], v[236:239], v[34:37]
	v_mfma_f32_16x16x32_bf16 v[26:29], v[216:219], v[236:239], v[26:29]
	v_mfma_f32_16x16x32_bf16 v[18:21], v[208:211], v[244:247], v[18:21]
	ds_read_b128 v[142:145], v167 offset:3072
	v_mfma_f32_16x16x32_bf16 v[10:13], v[216:219], v[244:247], v[10:13]
	v_mfma_f32_16x16x32_bf16 v[6:9], v[208:211], v[220:223], v[6:9]
	v_mfma_f32_16x16x32_bf16 v[2:5], v[216:219], v[220:223], v[2:5]
	s_add_i32 s67, s67, 2
	s_add_u32 s38, s38, 0x100
	s_addc_u32 s39, s39, 0
	s_add_u32 s65, s65, 0x100
	s_addc_u32 s66, s66, 0
	s_cmp_gt_u32 s67, 29
	s_barrier
	s_cbranch_scc0 .LBB0_945
.Lp6_loop_exit:
	s_lshl_b32 s27, s36, 8
	s_add_i32 s38, s27, 0xffffc000
	s_lshr_b32 s38, s38, 4
	s_ashr_i32 s29, s36, 4
	s_or_b32 s38, s38, 4
	s_cmp_lt_i32 s36, 64
	s_cselect_b32 s29, s29, s38
	v_lshl_or_b32 v130, s62, 8, v165
	s_mul_hi_i32 s36, s29, 0xc000
	s_mul_i32 s29, s29, 0xc000
	v_add_u32_e32 v168, s27, v163
	s_add_u32 s38, s10, s29
	v_ashrrev_i32_e32 v131, 31, v130
	v_ashrrev_i32_e32 v169, 31, v168
	s_addc_u32 s39, s11, s36
	v_lshlrev_b64 v[158:159], 2, v[130:131]
	v_lshlrev_b64 v[238:239], 13, v[168:169]
	v_or_b32_e32 v188, 16, v168
	v_or_b32_e32 v204, 32, v168
	v_or_b32_e32 v168, 48, v168
	v_lshl_add_u64 v[130:131], s[38:39], 0, v[158:159]
	v_ashrrev_i32_e32 v189, 31, v188
	v_ashrrev_i32_e32 v205, 31, v204
	v_ashrrev_i32_e32 v169, 31, v168
	v_lshl_add_u64 v[132:133], v[130:131], 0, s[16:17]
	v_add_co_u32_e32 v130, vcc, s61, v130
	v_lshl_add_u64 v[236:237], s[6:7], 0, v[158:159]
	v_lshlrev_b64 v[240:241], 13, v[188:189]
	v_lshlrev_b64 v[242:243], 13, v[204:205]
	v_lshlrev_b64 v[168:169], 13, v[168:169]
	v_addc_co_u32_e32 v131, vcc, 0, v131, vcc
	v_lshl_add_u64 v[184:185], v[236:237], 0, v[238:239]
	v_lshl_add_u64 v[200:201], v[236:237], 0, v[240:241]
	v_lshl_add_u64 v[216:217], v[236:237], 0, v[242:243]
	v_lshl_add_u64 v[232:233], v[236:237], 0, v[168:169]
	global_load_dwordx4 v[138:141], v[132:133], off offset:64
	global_load_dwordx4 v[134:137], v[132:133], off offset:512
	global_load_dwordx4 v[142:145], v[130:131], off
	s_nop 0
	global_load_dwordx4 v[130:133], v[132:133], off offset:576
	s_nop 0
	global_load_dwordx4 v[172:175], v[184:185], off
	global_load_dwordx4 v[176:179], v[184:185], off offset:64
	global_load_dwordx4 v[180:183], v[184:185], off offset:512
	s_nop 0
	global_load_dwordx4 v[184:187], v[184:185], off offset:576
	s_nop 0
	global_load_dwordx4 v[188:191], v[200:201], off
	global_load_dwordx4 v[192:195], v[200:201], off offset:64
	global_load_dwordx4 v[196:199], v[200:201], off offset:512
	s_nop 0
	global_load_dwordx4 v[200:203], v[200:201], off offset:576
	s_nop 0
	global_load_dwordx4 v[204:207], v[216:217], off
	global_load_dwordx4 v[208:211], v[216:217], off offset:64
	global_load_dwordx4 v[212:215], v[216:217], off offset:512
	s_nop 0
	global_load_dwordx4 v[216:219], v[216:217], off offset:576
	s_nop 0
	global_load_dwordx4 v[220:223], v[232:233], off
	global_load_dwordx4 v[224:227], v[232:233], off offset:64
	global_load_dwordx4 v[228:231], v[232:233], off offset:512
	s_nop 0
	global_load_dwordx4 v[232:235], v[232:233], off offset:576
	v_lshl_add_u64 v[244:245], s[8:9], 0, v[238:239]
	v_lshl_add_u64 v[244:245], v[244:245], 0, v[158:159]
	s_waitcnt vmcnt(0)
	v_pk_fma_f32 v[112:113], v[112:113], v[132:133], v[186:187]
	v_pk_fma_f32 v[110:111], v[110:111], v[130:131], v[184:185]
	v_pk_fma_f32 v[120:121], v[120:121], v[136:137], v[182:183]
	v_pk_fma_f32 v[118:119], v[118:119], v[134:135], v[180:181]
	global_store_dwordx4 v[244:245], v[110:113], off offset:576
	global_store_dwordx4 v[244:245], v[118:121], off offset:512
	v_pk_fma_f32 v[96:97], v[96:97], v[132:133], v[202:203]
	v_lshl_add_u64 v[110:111], s[8:9], 0, v[240:241]
	v_lshl_add_u64 v[118:119], v[110:111], 0, v[158:159]
	v_pk_fma_f32 v[94:95], v[94:95], v[130:131], v[200:201]
	v_pk_fma_f32 v[104:105], v[104:105], v[136:137], v[198:199]
	v_pk_fma_f32 v[102:103], v[102:103], v[134:135], v[196:197]
	global_store_dwordx4 v[118:119], v[94:97], off offset:576
	global_store_dwordx4 v[118:119], v[102:105], off offset:512
	v_pk_fma_f32 v[80:81], v[80:81], v[132:133], v[218:219]
	v_lshl_add_u64 v[94:95], s[8:9], 0, v[242:243]
	v_lshl_add_u64 v[102:103], v[94:95], 0, v[158:159]
	v_pk_fma_f32 v[78:79], v[78:79], v[130:131], v[216:217]
	v_pk_fma_f32 v[88:89], v[88:89], v[136:137], v[214:215]
	v_pk_fma_f32 v[86:87], v[86:87], v[134:135], v[212:213]
	global_store_dwordx4 v[102:103], v[78:81], off offset:576
	v_pk_fma_f32 v[128:129], v[128:129], v[144:145], v[174:175]
	v_pk_fma_f32 v[126:127], v[126:127], v[142:143], v[172:173]
	v_lshl_add_u64 v[78:79], s[8:9], 0, v[168:169]
	v_pk_fma_f32 v[124:125], v[124:125], v[140:141], v[178:179]
	v_pk_fma_f32 v[122:123], v[122:123], v[138:139], v[176:177]
	v_pk_fma_f32 v[112:113], v[116:117], v[144:145], v[190:191]
	v_pk_fma_f32 v[110:111], v[114:115], v[142:143], v[188:189]
	v_pk_fma_f32 v[108:109], v[108:109], v[140:141], v[194:195]
	v_pk_fma_f32 v[106:107], v[106:107], v[138:139], v[192:193]
	v_pk_fma_f32 v[96:97], v[100:101], v[144:145], v[206:207]
	v_pk_fma_f32 v[94:95], v[98:99], v[142:143], v[204:205]
	v_pk_fma_f32 v[92:93], v[92:93], v[140:141], v[210:211]
	v_pk_fma_f32 v[90:91], v[90:91], v[138:139], v[208:209]
	global_store_dwordx4 v[102:103], v[86:89], off offset:512
	v_pk_fma_f32 v[80:81], v[84:85], v[144:145], v[222:223]
	v_pk_fma_f32 v[76:77], v[76:77], v[140:141], v[226:227]
	v_lshl_add_u64 v[86:87], v[78:79], 0, v[158:159]
	v_pk_fma_f32 v[78:79], v[82:83], v[142:143], v[220:221]
	v_pk_fma_f32 v[74:75], v[74:75], v[138:139], v[224:225]
	v_pk_fma_f32 v[72:73], v[72:73], v[136:137], v[230:231]
	v_pk_fma_f32 v[70:71], v[70:71], v[134:135], v[228:229]
	v_pk_fma_f32 v[68:69], v[68:69], v[132:133], v[234:235]
	v_pk_fma_f32 v[66:67], v[66:67], v[130:131], v[232:233]
	v_lshl_add_u64 v[168:169], v[238:239], 0, s[18:19]
	v_lshl_add_u64 v[172:173], v[238:239], 0, s[20:21]
	v_lshl_add_u64 v[174:175], v[238:239], 0, s[22:23]
	v_lshl_add_u64 v[176:177], v[238:239], 0, s[24:25]
	global_store_dwordx4 v[244:245], v[126:129], off
	global_store_dwordx4 v[244:245], v[122:125], off offset:64
	global_store_dwordx4 v[118:119], v[110:113], off
	global_store_dwordx4 v[118:119], v[106:109], off offset:64
	global_store_dwordx4 v[102:103], v[94:97], off
	global_store_dwordx4 v[102:103], v[90:93], off offset:64
	global_store_dwordx4 v[86:87], v[78:81], off
	global_store_dwordx4 v[86:87], v[74:77], off offset:64
	global_store_dwordx4 v[86:87], v[70:73], off offset:512
	global_store_dwordx4 v[86:87], v[66:69], off offset:576
	v_lshl_add_u64 v[78:79], v[236:237], 0, v[168:169]
	v_lshl_add_u64 v[94:95], v[236:237], 0, v[172:173]
	v_lshl_add_u64 v[110:111], v[236:237], 0, v[174:175]
	v_lshl_add_u64 v[126:127], v[236:237], 0, v[176:177]
	global_load_dwordx4 v[66:69], v[78:79], off
	global_load_dwordx4 v[70:73], v[78:79], off offset:64
	global_load_dwordx4 v[74:77], v[78:79], off offset:512
	s_nop 0
	global_load_dwordx4 v[78:81], v[78:79], off offset:576
	s_nop 0
	global_load_dwordx4 v[82:85], v[94:95], off
	global_load_dwordx4 v[86:89], v[94:95], off offset:64
	global_load_dwordx4 v[90:93], v[94:95], off offset:512
	s_nop 0
	global_load_dwordx4 v[94:97], v[94:95], off offset:576
	s_nop 0
	global_load_dwordx4 v[98:101], v[110:111], off
	global_load_dwordx4 v[102:105], v[110:111], off offset:64
	global_load_dwordx4 v[106:109], v[110:111], off offset:512
	s_nop 0
	global_load_dwordx4 v[110:113], v[110:111], off offset:576
	s_nop 0
	global_load_dwordx4 v[114:117], v[126:127], off
	global_load_dwordx4 v[118:121], v[126:127], off offset:64
	global_load_dwordx4 v[122:125], v[126:127], off offset:512
	s_nop 0
	global_load_dwordx4 v[126:129], v[126:127], off offset:576
	v_lshl_add_u64 v[168:169], s[8:9], 0, v[168:169]
	v_lshl_add_u64 v[168:169], v[168:169], 0, v[158:159]
	s_waitcnt vmcnt(0)
	v_pk_fma_f32 v[44:45], v[44:45], v[132:133], v[80:81]
	v_pk_fma_f32 v[42:43], v[42:43], v[130:131], v[78:79]
	v_pk_fma_f32 v[52:53], v[52:53], v[136:137], v[76:77]
	v_pk_fma_f32 v[50:51], v[50:51], v[134:135], v[74:75]
	global_store_dwordx4 v[168:169], v[42:45], off offset:576
	global_store_dwordx4 v[168:169], v[50:53], off offset:512
	v_pk_fma_f32 v[28:29], v[28:29], v[132:133], v[96:97]
	v_lshl_add_u64 v[42:43], s[8:9], 0, v[172:173]
	v_lshl_add_u64 v[50:51], v[42:43], 0, v[158:159]
	v_pk_fma_f32 v[26:27], v[26:27], v[130:131], v[94:95]
	v_pk_fma_f32 v[36:37], v[36:37], v[136:137], v[92:93]
	v_pk_fma_f32 v[34:35], v[34:35], v[134:135], v[90:91]
	global_store_dwordx4 v[50:51], v[26:29], off offset:576
	global_store_dwordx4 v[50:51], v[34:37], off offset:512
	v_pk_fma_f32 v[12:13], v[12:13], v[132:133], v[112:113]
	v_lshl_add_u64 v[26:27], s[8:9], 0, v[174:175]
	v_lshl_add_u64 v[34:35], v[26:27], 0, v[158:159]
	v_pk_fma_f32 v[10:11], v[10:11], v[130:131], v[110:111]
	v_pk_fma_f32 v[20:21], v[20:21], v[136:137], v[108:109]
	v_pk_fma_f32 v[18:19], v[18:19], v[134:135], v[106:107]
	global_store_dwordx4 v[34:35], v[10:13], off offset:576
	v_pk_fma_f32 v[44:45], v[56:57], v[144:145], v[84:85]
	v_pk_fma_f32 v[42:43], v[54:55], v[142:143], v[82:83]
	v_lshl_add_u64 v[10:11], s[8:9], 0, v[176:177]
	v_pk_fma_f32 v[28:29], v[40:41], v[144:145], v[100:101]
	v_pk_fma_f32 v[26:27], v[38:39], v[142:143], v[98:99]
	global_store_dwordx4 v[34:35], v[18:21], off offset:512
	v_pk_fma_f32 v[12:13], v[24:25], v[144:145], v[116:117]
	v_pk_fma_f32 v[64:65], v[64:65], v[144:145], v[68:69]
	v_lshl_add_u64 v[18:19], v[10:11], 0, v[158:159]
	v_pk_fma_f32 v[10:11], v[22:23], v[142:143], v[114:115]
	v_pk_fma_f32 v[62:63], v[62:63], v[142:143], v[66:67]
	v_pk_fma_f32 v[60:61], v[60:61], v[140:141], v[72:73]
	v_pk_fma_f32 v[58:59], v[58:59], v[138:139], v[70:71]
	global_store_dwordx4 v[50:51], v[42:45], off
	global_store_dwordx4 v[34:35], v[26:29], off
	global_store_dwordx4 v[18:19], v[10:13], off
	v_pk_fma_f32 v[44:45], v[48:49], v[140:141], v[88:89]
	v_pk_fma_f32 v[42:43], v[46:47], v[138:139], v[86:87]
	v_pk_fma_f32 v[28:29], v[32:33], v[140:141], v[104:105]
	v_pk_fma_f32 v[26:27], v[30:31], v[138:139], v[102:103]
	v_pk_fma_f32 v[12:13], v[16:17], v[140:141], v[120:121]
	v_pk_fma_f32 v[10:11], v[14:15], v[138:139], v[118:119]
	v_pk_fma_f32 v[8:9], v[8:9], v[136:137], v[124:125]
	v_pk_fma_f32 v[6:7], v[6:7], v[134:135], v[122:123]
	v_pk_fma_f32 v[4:5], v[4:5], v[132:133], v[128:129]
	v_pk_fma_f32 v[2:3], v[2:3], v[130:131], v[126:127]
	s_and_b64 vcc, exec, s[4:5]
	s_mov_b32 s62, s26
	s_mov_b32 s36, s28
	s_mov_b64 s[40:41], s[34:35]
	s_mov_b64 s[38:39], s[30:31]
	global_store_dwordx4 v[168:169], v[62:65], off
	global_store_dwordx4 v[168:169], v[58:61], off offset:64
	global_store_dwordx4 v[50:51], v[42:45], off offset:64
	global_store_dwordx4 v[34:35], v[26:29], off offset:64
	global_store_dwordx4 v[18:19], v[10:13], off offset:64
	global_store_dwordx4 v[18:19], v[6:9], off offset:512
	global_store_dwordx4 v[18:19], v[2:5], off offset:576
	s_cbranch_vccz .LBB0_938
	s_setprio 0
	s_waitcnt vmcnt(0)
	s_cmpk_gt_u32 s45, 0xff
	s_cbranch_scc1 .LBB0_949
	s_barrier

.LBB0_1285:
	s_mov_b64 s[18:19], 0x80
	s_lshl_b32 s6, s6, 5
	s_add_i32 m0, s43, 0x18000
	v_lshl_add_u64 v[8:9], v[8:9], 0, s[18:19]
	s_lshl_b32 s8, s4, 13
	s_and_b32 s9, s6, 0x60
	s_waitcnt vmcnt(4)
	s_barrier
	global_load_lds_dwordx4 v[8:9], off
	v_lshl_add_u64 v[6:7], v[6:7], 0, s[18:19]
	s_add_i32 m0, s43, 0x1a000
	s_add_i32 s48, s43, 0x8000
	s_add_i32 s49, s43, 0xa000
	global_load_lds_dwordx4 v[6:7], off
	v_lshl_add_u64 v[4:5], v[4:5], 0, s[18:19]
	s_mov_b32 m0, s48
	s_add_u32 s6, s30, 0x160080
	global_load_lds_dwordx4 v[4:5], off
	v_lshl_add_u64 v[2:3], v[2:3], 0, s[18:19]
	s_mov_b32 m0, s49
	s_addc_u32 s7, s31, 0
	global_load_lds_dwordx4 v[2:3], off
	s_add_i32 m0, s43, 0x1c000
	v_lshl_add_u64 v[2:3], s[6:7], 0, v[146:147]
	global_load_lds_dwordx4 v[2:3], off
	v_lshl_add_u64 v[2:3], s[6:7], 0, v[148:149]
	s_add_i32 m0, s43, 0x1e000
	v_and_b32_e32 v4, 15, v0
	global_load_lds_dwordx4 v[2:3], off
	v_lshlrev_b32_e32 v3, 2, v4
	v_lshl_or_b32 v2, v4, 6, v167
	v_and_b32_e32 v3, 32, v3
	s_waitcnt vmcnt(6)
	v_bitop3_b32 v2, v2, s8, v3 bitop3:0xde
	v_lshl_or_b32 v173, s9, 7, v170
	v_bfe_u32 v3, v0, 4, 2
	s_add_i32 s51, 0, 0x10000
	s_add_i32 s52, 0, 0x14000
	s_sext_i32_i8 s57, s5
	v_lshl_or_b32 v172, s4, 6, v4
	s_ashr_i32 s50, s33, 31
	v_lshl_or_b32 v174, v3, 2, s9
	v_add3_u32 v150, v165, v1, v164
	v_mov_b32_e32 v151, v147
	v_add3_u32 v152, v166, v1, v164
	v_mov_b32_e32 v153, v147
	v_mov_b64_e32 v[154:155], 0x200
	v_mov_b64_e32 v[156:157], 0x1ff
	v_add_u32_e32 v175, s51, v173
	v_add_u32_e32 v176, 0, v2
	v_add_u32_e32 v177, s52, v173
	s_mov_b64 s[20:21], 0x610a000
	s_mov_b32 s53, 0x610a000
	s_mov_b64 s[22:23], 0x100000
	s_mov_b64 s[24:25], 0x120000
	s_mov_b64 s[26:27], 0x140000
	s_barrier
	s_cmpk_lt_u32 s40, 0x1000
	s_cbranch_scc0 .Lp10_prio_done
	s_setprio 1
.Lp10_prio_done:
.LBB0_1286:
	s_add_i32 s47, s47, 1
	s_mul_i32 s4, s47, s50
	s_mul_hi_u32 s5, s47, s33
	s_add_i32 s5, s5, s4
	s_mul_i32 s4, s47, s33
	s_add_u32 s8, s4, s37
	s_addc_u32 s9, s5, s39
	v_cmp_gt_i64_e64 s[4:5], s[8:9], v[156:157]
	v_cmp_lt_i64_e64 s[6:7], s[8:9], v[154:155]
	s_and_b64 vcc, exec, s[4:5]
	s_cbranch_vccnz .LBB0_1292
	s_ashr_i32 s9, s8, 31
	s_lshr_b32 s9, s9, 29
	s_add_i32 s34, s8, s9
	s_and_b32 s9, s34, -8
	s_sub_i32 s35, s8, s9
	s_cmp_gt_i32 s35, -1
	s_mov_b64 s[8:9], -1
	s_cbranch_scc0 .LBB0_1289
	s_lshl_b32 s54, s35, 6
	s_mov_b64 s[8:9], 0

.LBB0_1296:
	v_add_u32_e32 v154, 0x18000, v173
	v_add_u32_e32 v155, 0x1c000, v173
	ds_read_b128 v[126:129], v175
	ds_read_b128 v[134:137], v175 offset:1024
	ds_read_b128 v[138:141], v175 offset:2048
	ds_read_b128 v[142:145], v175 offset:3072
	ds_read_b128 v[158:161], v176
	ds_read_b128 v[178:181], v176 offset:1024
	ds_read_b128 v[182:185], v176 offset:2048
	ds_read_b128 v[186:189], v176 offset:3072
	ds_read_b128 v[190:193], v176 offset:4096
	ds_read_b128 v[194:197], v176 offset:5120
	ds_read_b128 v[198:201], v176 offset:6144
	ds_read_b128 v[202:205], v176 offset:7168
	s_add_u32 s28, s28, 0x160080
	s_addc_u32 s29, s29, 0
	s_add_u32 s58, s30, 0x100
	s_addc_u32 s59, s31, 0
	s_mov_b32 s60, -2
	s_add_u32 s30, s28, 0xffea0080
	s_addc_u32 s31, s29, -1
	s_cmpk_eq_i32 s60, 0x54
	s_cselect_b32 s35, s7, s31
	s_cselect_b32 s34, s6, s30
	s_cselect_b32 s31, s9, s59
	s_cselect_b32 s30, s8, s58
	s_add_i32 m0, s43, 0xc000
	s_nop 0
	global_load_lds_dwordx4 v150, s[28:29]
	s_add_i32 m0, s43, 0xe000
	s_nop 0
	global_load_lds_dwordx4 v152, s[28:29]
	s_waitcnt vmcnt(10)
	s_barrier
	s_waitcnt lgkmcnt(0)
	v_mfma_f32_16x16x32_bf16 v[130:133], v[126:129], v[158:161], 0
	ds_read_b128 v[206:209], v177
	v_mfma_f32_16x16x32_bf16 v[122:125], v[138:141], v[158:161], 0
	v_mfma_f32_16x16x32_bf16 v[118:121], v[126:129], v[182:185], 0
	v_mfma_f32_16x16x32_bf16 v[114:117], v[138:141], v[182:185], 0
	v_mfma_f32_16x16x32_bf16 v[102:105], v[126:129], v[190:193], 0
	ds_read_b128 v[210:213], v177 offset:1024
	v_mfma_f32_16x16x32_bf16 v[98:101], v[138:141], v[190:193], 0
	v_mfma_f32_16x16x32_bf16 v[86:89], v[126:129], v[198:201], 0
	v_mfma_f32_16x16x32_bf16 v[82:85], v[138:141], v[198:201], 0
	v_mfma_f32_16x16x32_bf16 v[130:133], v[134:137], v[178:181], v[130:133]
	ds_read_b128 v[214:217], v177 offset:2048
	v_mfma_f32_16x16x32_bf16 v[122:125], v[142:145], v[178:181], v[122:125]
	v_mfma_f32_16x16x32_bf16 v[118:121], v[134:137], v[186:189], v[118:121]
	v_mfma_f32_16x16x32_bf16 v[114:117], v[142:145], v[186:189], v[114:117]
	v_mfma_f32_16x16x32_bf16 v[102:105], v[134:137], v[194:197], v[102:105]
	ds_read_b128 v[218:221], v177 offset:3072
	v_mfma_f32_16x16x32_bf16 v[98:101], v[142:145], v[194:197], v[98:101]
	v_mfma_f32_16x16x32_bf16 v[86:89], v[134:137], v[202:205], v[86:89]
	v_mfma_f32_16x16x32_bf16 v[82:85], v[142:145], v[202:205], v[82:85]
	s_barrier
	s_add_i32 s61, s51, s40
	s_add_u32 s96, s30, 0x80
	s_addc_u32 s97, s31, 0
	s_mov_b32 m0, s61
	s_nop 0
	global_load_lds_dwordx4 v146, s[30:31]
	s_add_i32 m0, s61, 0x2000
	s_nop 0
	global_load_lds_dwordx4 v148, s[30:31]
	s_waitcnt vmcnt(10)
	s_barrier
	s_waitcnt lgkmcnt(0)
	v_mfma_f32_16x16x32_bf16 v[110:113], v[206:209], v[158:161], 0
	ds_read_b128 v[226:229], v176 offset:16384
	v_mfma_f32_16x16x32_bf16 v[106:109], v[214:217], v[158:161], 0
	v_mfma_f32_16x16x32_bf16 v[94:97], v[206:209], v[182:185], 0
	ds_read_b128 v[230:233], v176 offset:17408
	v_mfma_f32_16x16x32_bf16 v[90:93], v[214:217], v[182:185], 0
	v_mfma_f32_16x16x32_bf16 v[78:81], v[206:209], v[190:193], 0
	ds_read_b128 v[234:237], v176 offset:18432
	v_mfma_f32_16x16x32_bf16 v[74:77], v[214:217], v[190:193], 0
	v_mfma_f32_16x16x32_bf16 v[70:73], v[206:209], v[198:201], 0
	ds_read_b128 v[238:241], v176 offset:19456
	v_mfma_f32_16x16x32_bf16 v[66:69], v[214:217], v[198:201], 0
	v_mfma_f32_16x16x32_bf16 v[110:113], v[210:213], v[178:181], v[110:113]
	ds_read_b128 v[242:245], v176 offset:20480
	v_mfma_f32_16x16x32_bf16 v[106:109], v[218:221], v[178:181], v[106:109]
	v_mfma_f32_16x16x32_bf16 v[94:97], v[210:213], v[186:189], v[94:97]
	ds_read_b128 v[246:249], v176 offset:21504
	v_mfma_f32_16x16x32_bf16 v[90:93], v[218:221], v[186:189], v[90:93]
	v_mfma_f32_16x16x32_bf16 v[78:81], v[210:213], v[194:197], v[78:81]
	ds_read_b128 v[250:253], v176 offset:22528
	v_mfma_f32_16x16x32_bf16 v[74:77], v[218:221], v[194:197], v[74:77]
	v_mfma_f32_16x16x32_bf16 v[70:73], v[210:213], v[202:205], v[70:73]
	ds_read_b128 v[222:225], v176 offset:23552
	v_mfma_f32_16x16x32_bf16 v[66:69], v[218:221], v[202:205], v[66:69]
	s_barrier
	s_mov_b32 m0, s43
	s_add_u32 s94, s34, 0x80
	s_addc_u32 s95, s35, 0
	global_load_lds_dwordx4 v146, s[34:35]
	s_mov_b32 m0, s44
	s_nop 0
	global_load_lds_dwordx4 v148, s[34:35]
	s_waitcnt vmcnt(8)
	s_barrier
	s_waitcnt lgkmcnt(0)
	v_mfma_f32_16x16x32_bf16 v[62:65], v[126:129], v[226:229], 0
	ds_read_b128 v[158:161], v176 offset:32768
	v_mfma_f32_16x16x32_bf16 v[58:61], v[138:141], v[226:229], 0
	v_mfma_f32_16x16x32_bf16 v[54:57], v[126:129], v[234:237], 0
	ds_read_b128 v[178:181], v176 offset:33792
	v_mfma_f32_16x16x32_bf16 v[46:49], v[138:141], v[234:237], 0
	v_mfma_f32_16x16x32_bf16 v[38:41], v[126:129], v[242:245], 0
	ds_read_b128 v[182:185], v176 offset:34816
	v_mfma_f32_16x16x32_bf16 v[30:33], v[138:141], v[242:245], 0
	v_mfma_f32_16x16x32_bf16 v[22:25], v[126:129], v[250:253], 0
	ds_read_b128 v[186:189], v176 offset:35840
	v_mfma_f32_16x16x32_bf16 v[14:17], v[138:141], v[250:253], 0
	v_mfma_f32_16x16x32_bf16 v[62:65], v[134:137], v[230:233], v[62:65]
	ds_read_b128 v[190:193], v176 offset:36864
	v_mfma_f32_16x16x32_bf16 v[58:61], v[142:145], v[230:233], v[58:61]
	v_mfma_f32_16x16x32_bf16 v[54:57], v[134:137], v[238:241], v[54:57]
	ds_read_b128 v[194:197], v176 offset:37888
	v_mfma_f32_16x16x32_bf16 v[46:49], v[142:145], v[238:241], v[46:49]
	v_mfma_f32_16x16x32_bf16 v[38:41], v[134:137], v[246:249], v[38:41]
	ds_read_b128 v[198:201], v176 offset:38912
	v_mfma_f32_16x16x32_bf16 v[30:33], v[142:145], v[246:249], v[30:33]
	v_mfma_f32_16x16x32_bf16 v[22:25], v[134:137], v[222:225], v[22:25]
	ds_read_b128 v[202:205], v176 offset:39936
	v_mfma_f32_16x16x32_bf16 v[14:17], v[142:145], v[222:225], v[14:17]
	s_barrier
	s_add_u32 s62, s30, 0x160000
	s_addc_u32 s63, s31, 0
	s_add_i32 s61, s52, s40
	s_mov_b32 m0, s61
	s_nop 0
	global_load_lds_dwordx4 v146, s[62:63]
	s_add_i32 m0, s61, 0x2000
	s_nop 0
	global_load_lds_dwordx4 v148, s[62:63]
	s_waitcnt vmcnt(10)
	s_barrier
	s_waitcnt lgkmcnt(0)
	v_mfma_f32_16x16x32_bf16 v[50:53], v[206:209], v[226:229], 0
	ds_read_b128 v[126:129], v154
	v_mfma_f32_16x16x32_bf16 v[42:45], v[214:217], v[226:229], 0
	v_mfma_f32_16x16x32_bf16 v[34:37], v[206:209], v[234:237], 0
	v_mfma_f32_16x16x32_bf16 v[26:29], v[214:217], v[234:237], 0
	v_mfma_f32_16x16x32_bf16 v[18:21], v[206:209], v[242:245], 0
	ds_read_b128 v[134:137], v154 offset:1024
	v_mfma_f32_16x16x32_bf16 v[10:13], v[214:217], v[242:245], 0
	v_mfma_f32_16x16x32_bf16 v[6:9], v[206:209], v[250:253], 0
	v_mfma_f32_16x16x32_bf16 v[2:5], v[214:217], v[250:253], 0
	v_mfma_f32_16x16x32_bf16 v[50:53], v[210:213], v[230:233], v[50:53]
	ds_read_b128 v[138:141], v154 offset:2048
	v_mfma_f32_16x16x32_bf16 v[42:45], v[218:221], v[230:233], v[42:45]
	v_mfma_f32_16x16x32_bf16 v[34:37], v[210:213], v[238:241], v[34:37]
	v_mfma_f32_16x16x32_bf16 v[26:29], v[218:221], v[238:241], v[26:29]
	v_mfma_f32_16x16x32_bf16 v[18:21], v[210:213], v[246:249], v[18:21]
	ds_read_b128 v[142:145], v154 offset:3072
	v_mfma_f32_16x16x32_bf16 v[10:13], v[218:221], v[246:249], v[10:13]
	v_mfma_f32_16x16x32_bf16 v[6:9], v[210:213], v[222:225], v[6:9]
	v_mfma_f32_16x16x32_bf16 v[2:5], v[218:221], v[222:225], v[2:5]
	s_barrier
	s_add_i32 s61, 0, 0x18000
	s_add_u32 s34, s34, 0x160000
	s_addc_u32 s35, s35, 0
	s_mov_b32 m0, s45
	s_nop 0
	global_load_lds_dwordx4 v146, s[34:35]
	s_mov_b32 m0, s46
	s_nop 0
	global_load_lds_dwordx4 v148, s[34:35]
	s_waitcnt vmcnt(10)
	s_barrier
	s_waitcnt lgkmcnt(0)
	v_mfma_f32_16x16x32_bf16 v[130:133], v[126:129], v[158:161], v[130:133]
	ds_read_b128 v[206:209], v155
	v_mfma_f32_16x16x32_bf16 v[122:125], v[138:141], v[158:161], v[122:125]
	v_mfma_f32_16x16x32_bf16 v[118:121], v[126:129], v[182:185], v[118:121]
	v_mfma_f32_16x16x32_bf16 v[114:117], v[138:141], v[182:185], v[114:117]
	v_mfma_f32_16x16x32_bf16 v[102:105], v[126:129], v[190:193], v[102:105]
	ds_read_b128 v[210:213], v155 offset:1024
	v_mfma_f32_16x16x32_bf16 v[98:101], v[138:141], v[190:193], v[98:101]
	v_mfma_f32_16x16x32_bf16 v[86:89], v[126:129], v[198:201], v[86:89]
	v_mfma_f32_16x16x32_bf16 v[82:85], v[138:141], v[198:201], v[82:85]
	v_mfma_f32_16x16x32_bf16 v[130:133], v[134:137], v[178:181], v[130:133]
	ds_read_b128 v[214:217], v155 offset:2048
	v_mfma_f32_16x16x32_bf16 v[122:125], v[142:145], v[178:181], v[122:125]
	v_mfma_f32_16x16x32_bf16 v[118:121], v[134:137], v[186:189], v[118:121]
	v_mfma_f32_16x16x32_bf16 v[114:117], v[142:145], v[186:189], v[114:117]
	v_mfma_f32_16x16x32_bf16 v[102:105], v[134:137], v[194:197], v[102:105]
	ds_read_b128 v[218:221], v155 offset:3072
	v_mfma_f32_16x16x32_bf16 v[98:101], v[142:145], v[194:197], v[98:101]
	v_mfma_f32_16x16x32_bf16 v[86:89], v[134:137], v[202:205], v[86:89]
	v_mfma_f32_16x16x32_bf16 v[82:85], v[142:145], v[202:205], v[82:85]
	s_barrier
	s_add_i32 s84, 0, 0x1c000
	s_add_i32 s85, s61, s40
	s_mov_b32 m0, s85
	s_nop 0
	global_load_lds_dwordx4 v146, s[96:97]
	s_add_i32 m0, s85, 0x2000
	s_nop 0
	global_load_lds_dwordx4 v148, s[96:97]
	s_waitcnt vmcnt(10)
	s_barrier
	s_waitcnt lgkmcnt(0)
	v_mfma_f32_16x16x32_bf16 v[110:113], v[206:209], v[158:161], v[110:113]
	ds_read_b128 v[226:229], v176 offset:49152
	v_mfma_f32_16x16x32_bf16 v[106:109], v[214:217], v[158:161], v[106:109]
	v_mfma_f32_16x16x32_bf16 v[94:97], v[206:209], v[182:185], v[94:97]
	ds_read_b128 v[230:233], v176 offset:50176
	v_mfma_f32_16x16x32_bf16 v[90:93], v[214:217], v[182:185], v[90:93]
	v_mfma_f32_16x16x32_bf16 v[78:81], v[206:209], v[190:193], v[78:81]
	ds_read_b128 v[234:237], v176 offset:51200
	v_mfma_f32_16x16x32_bf16 v[74:77], v[214:217], v[190:193], v[74:77]
	v_mfma_f32_16x16x32_bf16 v[70:73], v[206:209], v[198:201], v[70:73]
	ds_read_b128 v[238:241], v176 offset:52224
	v_mfma_f32_16x16x32_bf16 v[66:69], v[214:217], v[198:201], v[66:69]
	v_mfma_f32_16x16x32_bf16 v[110:113], v[210:213], v[178:181], v[110:113]
	ds_read_b128 v[242:245], v176 offset:53248
	v_mfma_f32_16x16x32_bf16 v[106:109], v[218:221], v[178:181], v[106:109]
	v_mfma_f32_16x16x32_bf16 v[94:97], v[210:213], v[186:189], v[94:97]
	ds_read_b128 v[246:249], v176 offset:54272
	v_mfma_f32_16x16x32_bf16 v[90:93], v[218:221], v[186:189], v[90:93]
	v_mfma_f32_16x16x32_bf16 v[78:81], v[210:213], v[194:197], v[78:81]
	ds_read_b128 v[250:253], v176 offset:55296
	v_mfma_f32_16x16x32_bf16 v[74:77], v[218:221], v[194:197], v[74:77]
	v_mfma_f32_16x16x32_bf16 v[70:73], v[210:213], v[202:205], v[70:73]
	ds_read_b128 v[222:225], v176 offset:56320
	v_mfma_f32_16x16x32_bf16 v[66:69], v[218:221], v[202:205], v[66:69]
	s_barrier
	s_mov_b32 m0, s48
	s_nop 0
	global_load_lds_dwordx4 v146, s[94:95]
	s_mov_b32 m0, s49
	s_nop 0
	global_load_lds_dwordx4 v148, s[94:95]
	s_waitcnt vmcnt(8)
	s_barrier
	s_waitcnt lgkmcnt(0)
	v_mfma_f32_16x16x32_bf16 v[62:65], v[126:129], v[226:229], v[62:65]
	ds_read_b128 v[158:161], v176
	v_mfma_f32_16x16x32_bf16 v[58:61], v[138:141], v[226:229], v[58:61]
	v_mfma_f32_16x16x32_bf16 v[54:57], v[126:129], v[234:237], v[54:57]
	ds_read_b128 v[178:181], v176 offset:1024
	v_mfma_f32_16x16x32_bf16 v[46:49], v[138:141], v[234:237], v[46:49]
	v_mfma_f32_16x16x32_bf16 v[38:41], v[126:129], v[242:245], v[38:41]
	ds_read_b128 v[182:185], v176 offset:2048
	v_mfma_f32_16x16x32_bf16 v[30:33], v[138:141], v[242:245], v[30:33]
	v_mfma_f32_16x16x32_bf16 v[22:25], v[126:129], v[250:253], v[22:25]
	ds_read_b128 v[186:189], v176 offset:3072
	v_mfma_f32_16x16x32_bf16 v[14:17], v[138:141], v[250:253], v[14:17]
	v_mfma_f32_16x16x32_bf16 v[62:65], v[134:137], v[230:233], v[62:65]
	ds_read_b128 v[190:193], v176 offset:4096
	v_mfma_f32_16x16x32_bf16 v[58:61], v[142:145], v[230:233], v[58:61]
	v_mfma_f32_16x16x32_bf16 v[54:57], v[134:137], v[238:241], v[54:57]
	ds_read_b128 v[194:197], v176 offset:5120
	v_mfma_f32_16x16x32_bf16 v[46:49], v[142:145], v[238:241], v[46:49]
	v_mfma_f32_16x16x32_bf16 v[38:41], v[134:137], v[246:249], v[38:41]
	ds_read_b128 v[198:201], v176 offset:6144
	v_mfma_f32_16x16x32_bf16 v[30:33], v[142:145], v[246:249], v[30:33]
	v_mfma_f32_16x16x32_bf16 v[22:25], v[134:137], v[222:225], v[22:25]
	ds_read_b128 v[202:205], v176 offset:7168
	v_mfma_f32_16x16x32_bf16 v[14:17], v[142:145], v[222:225], v[14:17]
	s_barrier
	s_add_u32 s30, s30, 0x160080
	s_addc_u32 s31, s31, 0
	s_add_i32 s84, s84, s40
	s_mov_b32 m0, s84
	s_nop 0
	global_load_lds_dwordx4 v146, s[30:31]
	s_add_i32 m0, s84, 0x2000
	s_nop 0
	global_load_lds_dwordx4 v148, s[30:31]
	s_waitcnt vmcnt(10)
	s_barrier
	s_waitcnt lgkmcnt(0)
	v_mfma_f32_16x16x32_bf16 v[50:53], v[206:209], v[226:229], v[50:53]
	ds_read_b128 v[126:129], v175
	v_mfma_f32_16x16x32_bf16 v[42:45], v[214:217], v[226:229], v[42:45]
	v_mfma_f32_16x16x32_bf16 v[34:37], v[206:209], v[234:237], v[34:37]
	v_mfma_f32_16x16x32_bf16 v[26:29], v[214:217], v[234:237], v[26:29]
	v_mfma_f32_16x16x32_bf16 v[18:21], v[206:209], v[242:245], v[18:21]
	ds_read_b128 v[134:137], v175 offset:1024
	v_mfma_f32_16x16x32_bf16 v[10:13], v[214:217], v[242:245], v[10:13]
	v_mfma_f32_16x16x32_bf16 v[6:9], v[206:209], v[250:253], v[6:9]
	v_mfma_f32_16x16x32_bf16 v[2:5], v[214:217], v[250:253], v[2:5]
	v_mfma_f32_16x16x32_bf16 v[50:53], v[210:213], v[230:233], v[50:53]
	ds_read_b128 v[138:141], v175 offset:2048
	v_mfma_f32_16x16x32_bf16 v[42:45], v[218:221], v[230:233], v[42:45]
	v_mfma_f32_16x16x32_bf16 v[34:37], v[210:213], v[238:241], v[34:37]
	v_mfma_f32_16x16x32_bf16 v[26:29], v[218:221], v[238:241], v[26:29]
	v_mfma_f32_16x16x32_bf16 v[18:21], v[210:213], v[246:249], v[18:21]
	ds_read_b128 v[142:145], v175 offset:3072
	v_mfma_f32_16x16x32_bf16 v[10:13], v[218:221], v[246:249], v[10:13]
	v_mfma_f32_16x16x32_bf16 v[6:9], v[210:213], v[222:225], v[6:9]
	v_mfma_f32_16x16x32_bf16 v[2:5], v[218:221], v[222:225], v[2:5]
	s_add_i32 s60, s60, 2
	s_add_u32 s28, s28, 0x100
	s_addc_u32 s29, s29, 0
	s_add_u32 s58, s58, 0x100
	s_addc_u32 s59, s59, 0
	s_cmpk_gt_u32 s60, 0x55
	s_barrier
	s_cbranch_scc0 .LBB0_1297
	s_branch .Lp10_loop_exit
.LBB0_1297:
	s_add_u32 s30, s28, 0xffea0080
	s_addc_u32 s31, s29, -1
	s_cmpk_eq_i32 s60, 0x54
	s_cselect_b32 s35, s7, s31
	s_cselect_b32 s34, s6, s30
	s_cselect_b32 s31, s9, s59
	s_cselect_b32 s30, s8, s58
	s_add_i32 m0, s43, 0xc000
	s_nop 0
	global_load_lds_dwordx4 v150, s[28:29]
	s_add_i32 m0, s43, 0xe000
	s_nop 0
	global_load_lds_dwordx4 v152, s[28:29]
	s_waitcnt vmcnt(10)
	s_barrier
	s_waitcnt lgkmcnt(0)
	v_mfma_f32_16x16x32_bf16 v[130:133], v[126:129], v[158:161], v[130:133]
	ds_read_b128 v[206:209], v177
	v_mfma_f32_16x16x32_bf16 v[122:125], v[138:141], v[158:161], v[122:125]
	v_mfma_f32_16x16x32_bf16 v[118:121], v[126:129], v[182:185], v[118:121]
	v_mfma_f32_16x16x32_bf16 v[114:117], v[138:141], v[182:185], v[114:117]
	v_mfma_f32_16x16x32_bf16 v[102:105], v[126:129], v[190:193], v[102:105]
	ds_read_b128 v[210:213], v177 offset:1024
	v_mfma_f32_16x16x32_bf16 v[98:101], v[138:141], v[190:193], v[98:101]
	v_mfma_f32_16x16x32_bf16 v[86:89], v[126:129], v[198:201], v[86:89]
	v_mfma_f32_16x16x32_bf16 v[82:85], v[138:141], v[198:201], v[82:85]
	v_mfma_f32_16x16x32_bf16 v[130:133], v[134:137], v[178:181], v[130:133]
	ds_read_b128 v[214:217], v177 offset:2048
	v_mfma_f32_16x16x32_bf16 v[122:125], v[142:145], v[178:181], v[122:125]
	v_mfma_f32_16x16x32_bf16 v[118:121], v[134:137], v[186:189], v[118:121]
	v_mfma_f32_16x16x32_bf16 v[114:117], v[142:145], v[186:189], v[114:117]
	v_mfma_f32_16x16x32_bf16 v[102:105], v[134:137], v[194:197], v[102:105]
	ds_read_b128 v[218:221], v177 offset:3072
	v_mfma_f32_16x16x32_bf16 v[98:101], v[142:145], v[194:197], v[98:101]
	v_mfma_f32_16x16x32_bf16 v[86:89], v[134:137], v[202:205], v[86:89]
	v_mfma_f32_16x16x32_bf16 v[82:85], v[142:145], v[202:205], v[82:85]
	s_barrier
	s_add_i32 s61, s51, s40
	s_add_u32 s96, s30, 0x80
	s_addc_u32 s97, s31, 0
	s_mov_b32 m0, s61
	s_nop 0
	global_load_lds_dwordx4 v146, s[30:31]
	s_add_i32 m0, s61, 0x2000
	s_nop 0
	global_load_lds_dwordx4 v148, s[30:31]
	s_waitcnt vmcnt(10)
	s_barrier
	s_waitcnt lgkmcnt(0)
	v_mfma_f32_16x16x32_bf16 v[110:113], v[206:209], v[158:161], v[110:113]
	ds_read_b128 v[226:229], v176 offset:16384
	v_mfma_f32_16x16x32_bf16 v[106:109], v[214:217], v[158:161], v[106:109]
	v_mfma_f32_16x16x32_bf16 v[94:97], v[206:209], v[182:185], v[94:97]
	ds_read_b128 v[230:233], v176 offset:17408
	v_mfma_f32_16x16x32_bf16 v[90:93], v[214:217], v[182:185], v[90:93]
	v_mfma_f32_16x16x32_bf16 v[78:81], v[206:209], v[190:193], v[78:81]
	ds_read_b128 v[234:237], v176 offset:18432
	v_mfma_f32_16x16x32_bf16 v[74:77], v[214:217], v[190:193], v[74:77]
	v_mfma_f32_16x16x32_bf16 v[70:73], v[206:209], v[198:201], v[70:73]
	ds_read_b128 v[238:241], v176 offset:19456
	v_mfma_f32_16x16x32_bf16 v[66:69], v[214:217], v[198:201], v[66:69]
	v_mfma_f32_16x16x32_bf16 v[110:113], v[210:213], v[178:181], v[110:113]
	ds_read_b128 v[242:245], v176 offset:20480
	v_mfma_f32_16x16x32_bf16 v[106:109], v[218:221], v[178:181], v[106:109]
	v_mfma_f32_16x16x32_bf16 v[94:97], v[210:213], v[186:189], v[94:97]
	ds_read_b128 v[246:249], v176 offset:21504
	v_mfma_f32_16x16x32_bf16 v[90:93], v[218:221], v[186:189], v[90:93]
	v_mfma_f32_16x16x32_bf16 v[78:81], v[210:213], v[194:197], v[78:81]
	ds_read_b128 v[250:253], v176 offset:22528
	v_mfma_f32_16x16x32_bf16 v[74:77], v[218:221], v[194:197], v[74:77]
	v_mfma_f32_16x16x32_bf16 v[70:73], v[210:213], v[202:205], v[70:73]
	ds_read_b128 v[222:225], v176 offset:23552
	v_mfma_f32_16x16x32_bf16 v[66:69], v[218:221], v[202:205], v[66:69]
	s_barrier
	s_mov_b32 m0, s43
	s_add_u32 s94, s34, 0x80
	s_addc_u32 s95, s35, 0
	global_load_lds_dwordx4 v146, s[34:35]
	s_mov_b32 m0, s44
	s_nop 0
	global_load_lds_dwordx4 v148, s[34:35]
	s_waitcnt vmcnt(8)
	s_barrier
	s_waitcnt lgkmcnt(0)
	v_mfma_f32_16x16x32_bf16 v[62:65], v[126:129], v[226:229], v[62:65]
	ds_read_b128 v[158:161], v176 offset:32768
	v_mfma_f32_16x16x32_bf16 v[58:61], v[138:141], v[226:229], v[58:61]
	v_mfma_f32_16x16x32_bf16 v[54:57], v[126:129], v[234:237], v[54:57]
	ds_read_b128 v[178:181], v176 offset:33792
	v_mfma_f32_16x16x32_bf16 v[46:49], v[138:141], v[234:237], v[46:49]
	v_mfma_f32_16x16x32_bf16 v[38:41], v[126:129], v[242:245], v[38:41]
	ds_read_b128 v[182:185], v176 offset:34816
	v_mfma_f32_16x16x32_bf16 v[30:33], v[138:141], v[242:245], v[30:33]
	v_mfma_f32_16x16x32_bf16 v[22:25], v[126:129], v[250:253], v[22:25]
	ds_read_b128 v[186:189], v176 offset:35840
	v_mfma_f32_16x16x32_bf16 v[14:17], v[138:141], v[250:253], v[14:17]
	v_mfma_f32_16x16x32_bf16 v[62:65], v[134:137], v[230:233], v[62:65]
	ds_read_b128 v[190:193], v176 offset:36864
	v_mfma_f32_16x16x32_bf16 v[58:61], v[142:145], v[230:233], v[58:61]
	v_mfma_f32_16x16x32_bf16 v[54:57], v[134:137], v[238:241], v[54:57]
	ds_read_b128 v[194:197], v176 offset:37888
	v_mfma_f32_16x16x32_bf16 v[46:49], v[142:145], v[238:241], v[46:49]
	v_mfma_f32_16x16x32_bf16 v[38:41], v[134:137], v[246:249], v[38:41]
	ds_read_b128 v[198:201], v176 offset:38912
	v_mfma_f32_16x16x32_bf16 v[30:33], v[142:145], v[246:249], v[30:33]
	v_mfma_f32_16x16x32_bf16 v[22:25], v[134:137], v[222:225], v[22:25]
	ds_read_b128 v[202:205], v176 offset:39936
	v_mfma_f32_16x16x32_bf16 v[14:17], v[142:145], v[222:225], v[14:17]
	s_barrier
	s_add_u32 s62, s30, 0x160000
	s_addc_u32 s63, s31, 0
	s_add_i32 s61, s52, s40
	s_mov_b32 m0, s61
	s_nop 0
	global_load_lds_dwordx4 v146, s[62:63]
	s_add_i32 m0, s61, 0x2000
	s_nop 0
	global_load_lds_dwordx4 v148, s[62:63]
	s_waitcnt vmcnt(10)
	s_barrier
	s_waitcnt lgkmcnt(0)
	v_mfma_f32_16x16x32_bf16 v[50:53], v[206:209], v[226:229], v[50:53]
	ds_read_b128 v[126:129], v154
	v_mfma_f32_16x16x32_bf16 v[42:45], v[214:217], v[226:229], v[42:45]
	v_mfma_f32_16x16x32_bf16 v[34:37], v[206:209], v[234:237], v[34:37]
	v_mfma_f32_16x16x32_bf16 v[26:29], v[214:217], v[234:237], v[26:29]
	v_mfma_f32_16x16x32_bf16 v[18:21], v[206:209], v[242:245], v[18:21]
	ds_read_b128 v[134:137], v154 offset:1024
	v_mfma_f32_16x16x32_bf16 v[10:13], v[214:217], v[242:245], v[10:13]
	v_mfma_f32_16x16x32_bf16 v[6:9], v[206:209], v[250:253], v[6:9]
	v_mfma_f32_16x16x32_bf16 v[2:5], v[214:217], v[250:253], v[2:5]
	v_mfma_f32_16x16x32_bf16 v[50:53], v[210:213], v[230:233], v[50:53]
	ds_read_b128 v[138:141], v154 offset:2048
	v_mfma_f32_16x16x32_bf16 v[42:45], v[218:221], v[230:233], v[42:45]
	v_mfma_f32_16x16x32_bf16 v[34:37], v[210:213], v[238:241], v[34:37]
	v_mfma_f32_16x16x32_bf16 v[26:29], v[218:221], v[238:241], v[26:29]
	v_mfma_f32_16x16x32_bf16 v[18:21], v[210:213], v[246:249], v[18:21]
	ds_read_b128 v[142:145], v154 offset:3072
	v_mfma_f32_16x16x32_bf16 v[10:13], v[218:221], v[246:249], v[10:13]
	v_mfma_f32_16x16x32_bf16 v[6:9], v[210:213], v[222:225], v[6:9]
	v_mfma_f32_16x16x32_bf16 v[2:5], v[218:221], v[222:225], v[2:5]
	s_barrier
	s_add_i32 s61, 0, 0x18000
	s_add_u32 s34, s34, 0x160000
	s_addc_u32 s35, s35, 0
	s_mov_b32 m0, s45
	s_nop 0
	global_load_lds_dwordx4 v146, s[34:35]
	s_mov_b32 m0, s46
	s_nop 0
	global_load_lds_dwordx4 v148, s[34:35]
	s_waitcnt vmcnt(10)
	s_barrier
	s_waitcnt lgkmcnt(0)
	v_mfma_f32_16x16x32_bf16 v[130:133], v[126:129], v[158:161], v[130:133]
	ds_read_b128 v[206:209], v155
	v_mfma_f32_16x16x32_bf16 v[122:125], v[138:141], v[158:161], v[122:125]
	v_mfma_f32_16x16x32_bf16 v[118:121], v[126:129], v[182:185], v[118:121]
	v_mfma_f32_16x16x32_bf16 v[114:117], v[138:141], v[182:185], v[114:117]
	v_mfma_f32_16x16x32_bf16 v[102:105], v[126:129], v[190:193], v[102:105]
	ds_read_b128 v[210:213], v155 offset:1024
	v_mfma_f32_16x16x32_bf16 v[98:101], v[138:141], v[190:193], v[98:101]
	v_mfma_f32_16x16x32_bf16 v[86:89], v[126:129], v[198:201], v[86:89]
	v_mfma_f32_16x16x32_bf16 v[82:85], v[138:141], v[198:201], v[82:85]
	v_mfma_f32_16x16x32_bf16 v[130:133], v[134:137], v[178:181], v[130:133]
	ds_read_b128 v[214:217], v155 offset:2048
	v_mfma_f32_16x16x32_bf16 v[122:125], v[142:145], v[178:181], v[122:125]
	v_mfma_f32_16x16x32_bf16 v[118:121], v[134:137], v[186:189], v[118:121]
	v_mfma_f32_16x16x32_bf16 v[114:117], v[142:145], v[186:189], v[114:117]
	v_mfma_f32_16x16x32_bf16 v[102:105], v[134:137], v[194:197], v[102:105]
	ds_read_b128 v[218:221], v155 offset:3072
	v_mfma_f32_16x16x32_bf16 v[98:101], v[142:145], v[194:197], v[98:101]
	v_mfma_f32_16x16x32_bf16 v[86:89], v[134:137], v[202:205], v[86:89]
	v_mfma_f32_16x16x32_bf16 v[82:85], v[142:145], v[202:205], v[82:85]
	s_barrier
	s_add_i32 s84, 0, 0x1c000
	s_add_i32 s85, s61, s40
	s_mov_b32 m0, s85
	s_nop 0
	global_load_lds_dwordx4 v146, s[96:97]
	s_add_i32 m0, s85, 0x2000
	s_nop 0
	global_load_lds_dwordx4 v148, s[96:97]
	s_waitcnt vmcnt(10)
	s_barrier
	s_waitcnt lgkmcnt(0)
	v_mfma_f32_16x16x32_bf16 v[110:113], v[206:209], v[158:161], v[110:113]
	ds_read_b128 v[226:229], v176 offset:49152
	v_mfma_f32_16x16x32_bf16 v[106:109], v[214:217], v[158:161], v[106:109]
	v_mfma_f32_16x16x32_bf16 v[94:97], v[206:209], v[182:185], v[94:97]
	ds_read_b128 v[230:233], v176 offset:50176
	v_mfma_f32_16x16x32_bf16 v[90:93], v[214:217], v[182:185], v[90:93]
	v_mfma_f32_16x16x32_bf16 v[78:81], v[206:209], v[190:193], v[78:81]
	ds_read_b128 v[234:237], v176 offset:51200
	v_mfma_f32_16x16x32_bf16 v[74:77], v[214:217], v[190:193], v[74:77]
	v_mfma_f32_16x16x32_bf16 v[70:73], v[206:209], v[198:201], v[70:73]
	ds_read_b128 v[238:241], v176 offset:52224
	v_mfma_f32_16x16x32_bf16 v[66:69], v[214:217], v[198:201], v[66:69]
	v_mfma_f32_16x16x32_bf16 v[110:113], v[210:213], v[178:181], v[110:113]
	ds_read_b128 v[242:245], v176 offset:53248
	v_mfma_f32_16x16x32_bf16 v[106:109], v[218:221], v[178:181], v[106:109]
	v_mfma_f32_16x16x32_bf16 v[94:97], v[210:213], v[186:189], v[94:97]
	ds_read_b128 v[246:249], v176 offset:54272
	v_mfma_f32_16x16x32_bf16 v[90:93], v[218:221], v[186:189], v[90:93]
	v_mfma_f32_16x16x32_bf16 v[78:81], v[210:213], v[194:197], v[78:81]
	ds_read_b128 v[250:253], v176 offset:55296
	v_mfma_f32_16x16x32_bf16 v[74:77], v[218:221], v[194:197], v[74:77]
	v_mfma_f32_16x16x32_bf16 v[70:73], v[210:213], v[202:205], v[70:73]
	ds_read_b128 v[222:225], v176 offset:56320
	v_mfma_f32_16x16x32_bf16 v[66:69], v[218:221], v[202:205], v[66:69]
	s_barrier
	s_mov_b32 m0, s48
	s_nop 0
	global_load_lds_dwordx4 v146, s[94:95]
	s_mov_b32 m0, s49
	s_nop 0
	global_load_lds_dwordx4 v148, s[94:95]
	s_waitcnt vmcnt(8)
	s_barrier
	s_waitcnt lgkmcnt(0)
	v_mfma_f32_16x16x32_bf16 v[62:65], v[126:129], v[226:229], v[62:65]
	ds_read_b128 v[158:161], v176
	v_mfma_f32_16x16x32_bf16 v[58:61], v[138:141], v[226:229], v[58:61]
	v_mfma_f32_16x16x32_bf16 v[54:57], v[126:129], v[234:237], v[54:57]
	ds_read_b128 v[178:181], v176 offset:1024
	v_mfma_f32_16x16x32_bf16 v[46:49], v[138:141], v[234:237], v[46:49]
	v_mfma_f32_16x16x32_bf16 v[38:41], v[126:129], v[242:245], v[38:41]
	ds_read_b128 v[182:185], v176 offset:2048
	v_mfma_f32_16x16x32_bf16 v[30:33], v[138:141], v[242:245], v[30:33]
	v_mfma_f32_16x16x32_bf16 v[22:25], v[126:129], v[250:253], v[22:25]
	ds_read_b128 v[186:189], v176 offset:3072
	v_mfma_f32_16x16x32_bf16 v[14:17], v[138:141], v[250:253], v[14:17]
	v_mfma_f32_16x16x32_bf16 v[62:65], v[134:137], v[230:233], v[62:65]
	ds_read_b128 v[190:193], v176 offset:4096
	v_mfma_f32_16x16x32_bf16 v[58:61], v[142:145], v[230:233], v[58:61]
	v_mfma_f32_16x16x32_bf16 v[54:57], v[134:137], v[238:241], v[54:57]
	ds_read_b128 v[194:197], v176 offset:5120
	v_mfma_f32_16x16x32_bf16 v[46:49], v[142:145], v[238:241], v[46:49]
	v_mfma_f32_16x16x32_bf16 v[38:41], v[134:137], v[246:249], v[38:41]
	ds_read_b128 v[198:201], v176 offset:6144
	v_mfma_f32_16x16x32_bf16 v[30:33], v[142:145], v[246:249], v[30:33]
	v_mfma_f32_16x16x32_bf16 v[22:25], v[134:137], v[222:225], v[22:25]
	ds_read_b128 v[202:205], v176 offset:7168
	v_mfma_f32_16x16x32_bf16 v[14:17], v[142:145], v[222:225], v[14:17]
	s_barrier
	s_add_u32 s30, s30, 0x160080
	s_addc_u32 s31, s31, 0
	s_add_i32 s84, s84, s40
	s_mov_b32 m0, s84
	s_nop 0
	global_load_lds_dwordx4 v146, s[30:31]
	s_add_i32 m0, s84, 0x2000
	s_nop 0
	global_load_lds_dwordx4 v148, s[30:31]
	s_waitcnt vmcnt(10)
	s_barrier
	s_waitcnt lgkmcnt(0)
	v_mfma_f32_16x16x32_bf16 v[50:53], v[206:209], v[226:229], v[50:53]
	ds_read_b128 v[126:129], v175
	v_mfma_f32_16x16x32_bf16 v[42:45], v[214:217], v[226:229], v[42:45]
	v_mfma_f32_16x16x32_bf16 v[34:37], v[206:209], v[234:237], v[34:37]
	v_mfma_f32_16x16x32_bf16 v[26:29], v[214:217], v[234:237], v[26:29]
	v_mfma_f32_16x16x32_bf16 v[18:21], v[206:209], v[242:245], v[18:21]
	ds_read_b128 v[134:137], v175 offset:1024
	v_mfma_f32_16x16x32_bf16 v[10:13], v[214:217], v[242:245], v[10:13]
	v_mfma_f32_16x16x32_bf16 v[6:9], v[206:209], v[250:253], v[6:9]
	v_mfma_f32_16x16x32_bf16 v[2:5], v[214:217], v[250:253], v[2:5]
	v_mfma_f32_16x16x32_bf16 v[50:53], v[210:213], v[230:233], v[50:53]
	ds_read_b128 v[138:141], v175 offset:2048
	v_mfma_f32_16x16x32_bf16 v[42:45], v[218:221], v[230:233], v[42:45]
	v_mfma_f32_16x16x32_bf16 v[34:37], v[210:213], v[238:241], v[34:37]
	v_mfma_f32_16x16x32_bf16 v[26:29], v[218:221], v[238:241], v[26:29]
	v_mfma_f32_16x16x32_bf16 v[18:21], v[210:213], v[246:249], v[18:21]
	ds_read_b128 v[142:145], v175 offset:3072
	v_mfma_f32_16x16x32_bf16 v[10:13], v[218:221], v[246:249], v[10:13]
	v_mfma_f32_16x16x32_bf16 v[6:9], v[210:213], v[222:225], v[6:9]
	v_mfma_f32_16x16x32_bf16 v[2:5], v[218:221], v[222:225], v[2:5]
	s_add_i32 s60, s60, 2
	s_add_u32 s28, s28, 0x100
	s_addc_u32 s29, s29, 0
	s_add_u32 s58, s58, 0x100
	s_addc_u32 s59, s59, 0
	s_cmpk_gt_u32 s60, 0x55
	s_barrier
	s_cbranch_scc0 .LBB0_1297
.Lp10_loop_exit:
	s_lshl_b32 s30, s56, 8
	s_add_i32 s29, s30, 0xffffc000
	s_lshr_b32 s29, s29, 4
	s_ashr_i32 s28, s56, 4
	s_or_b32 s29, s29, 4
	s_cmp_lt_i32 s56, 64
	s_cselect_b32 s28, s28, s29
	v_lshl_or_b32 v126, s57, 8, v174
	s_mul_hi_i32 s29, s28, 0xc000
	s_mul_i32 s28, s28, 0xc000
	v_add_u32_e32 v168, s30, v172
	s_add_u32 s28, s12, s28
	v_ashrrev_i32_e32 v127, 31, v126
	v_ashrrev_i32_e32 v169, 31, v168
	s_addc_u32 s29, s13, s29
	v_lshlrev_b64 v[158:159], 2, v[126:127]
	v_lshlrev_b64 v[162:163], 13, v[168:169]
	v_or_b32_e32 v194, 16, v168
	v_or_b32_e32 v210, 32, v168
	v_or_b32_e32 v168, 48, v168
	v_lshl_add_u64 v[126:127], s[28:29], 0, v[158:159]
	v_ashrrev_i32_e32 v195, 31, v194
	v_ashrrev_i32_e32 v211, 31, v210
	v_ashrrev_i32_e32 v169, 31, v168
	v_lshl_add_u64 v[128:129], v[126:127], 0, s[20:21]
	v_add_co_u32_e32 v126, vcc, s53, v126
	v_lshl_add_u64 v[160:161], s[14:15], 0, v[158:159]
	v_lshlrev_b64 v[242:243], 13, v[194:195]
	v_lshlrev_b64 v[244:245], 13, v[210:211]
	v_lshlrev_b64 v[168:169], 13, v[168:169]
	v_addc_co_u32_e32 v127, vcc, 0, v127, vcc
	v_lshl_add_u64 v[190:191], v[160:161], 0, v[162:163]
	v_lshl_add_u64 v[206:207], v[160:161], 0, v[242:243]
	v_lshl_add_u64 v[222:223], v[160:161], 0, v[244:245]
	v_lshl_add_u64 v[238:239], v[160:161], 0, v[168:169]
	global_load_dwordx4 v[138:141], v[128:129], off offset:64
	global_load_dwordx4 v[134:137], v[128:129], off offset:512
	global_load_dwordx4 v[142:145], v[126:127], off
	s_nop 0
	global_load_dwordx4 v[126:129], v[128:129], off offset:576
	s_nop 0
	global_load_dwordx4 v[178:181], v[190:191], off
	global_load_dwordx4 v[182:185], v[190:191], off offset:64
	global_load_dwordx4 v[186:189], v[190:191], off offset:512
	s_nop 0
	global_load_dwordx4 v[190:193], v[190:191], off offset:576
	s_nop 0
	global_load_dwordx4 v[194:197], v[206:207], off
	global_load_dwordx4 v[198:201], v[206:207], off offset:64
	global_load_dwordx4 v[202:205], v[206:207], off offset:512
	s_nop 0
	global_load_dwordx4 v[206:209], v[206:207], off offset:576
	s_nop 0
	global_load_dwordx4 v[210:213], v[222:223], off
	global_load_dwordx4 v[214:217], v[222:223], off offset:64
	global_load_dwordx4 v[218:221], v[222:223], off offset:512
	s_nop 0
	global_load_dwordx4 v[222:225], v[222:223], off offset:576
	s_nop 0
	global_load_dwordx4 v[226:229], v[238:239], off
	global_load_dwordx4 v[230:233], v[238:239], off offset:64
	global_load_dwordx4 v[234:237], v[238:239], off offset:512
	s_nop 0
	global_load_dwordx4 v[238:241], v[238:239], off offset:576
	v_lshl_add_u64 v[246:247], s[14:15], 0, v[162:163]
	v_lshl_add_u64 v[246:247], v[246:247], 0, v[158:159]
	s_waitcnt vmcnt(0)
	v_pk_fma_f32 v[108:109], v[108:109], v[128:129], v[192:193]
	v_pk_fma_f32 v[106:107], v[106:107], v[126:127], v[190:191]
	v_pk_fma_f32 v[112:113], v[112:113], v[136:137], v[188:189]
	v_pk_fma_f32 v[110:111], v[110:111], v[134:135], v[186:187]
	global_store_dwordx4 v[246:247], v[106:109], off offset:576
	global_store_dwordx4 v[246:247], v[110:113], off offset:512
	v_pk_fma_f32 v[92:93], v[92:93], v[128:129], v[208:209]
	v_lshl_add_u64 v[106:107], s[14:15], 0, v[242:243]
	v_lshl_add_u64 v[110:111], v[106:107], 0, v[158:159]
	v_pk_fma_f32 v[90:91], v[90:91], v[126:127], v[206:207]
	v_pk_fma_f32 v[96:97], v[96:97], v[136:137], v[204:205]
	v_pk_fma_f32 v[94:95], v[94:95], v[134:135], v[202:203]
	global_store_dwordx4 v[110:111], v[90:93], off offset:576
	global_store_dwordx4 v[110:111], v[94:97], off offset:512
	v_pk_fma_f32 v[76:77], v[76:77], v[128:129], v[224:225]
	v_lshl_add_u64 v[90:91], s[14:15], 0, v[244:245]
	v_lshl_add_u64 v[94:95], v[90:91], 0, v[158:159]
	v_pk_fma_f32 v[74:75], v[74:75], v[126:127], v[222:223]
	v_pk_fma_f32 v[80:81], v[80:81], v[136:137], v[220:221]
	v_pk_fma_f32 v[78:79], v[78:79], v[134:135], v[218:219]
	global_store_dwordx4 v[94:95], v[74:77], off offset:576
	v_pk_fma_f32 v[108:109], v[120:121], v[144:145], v[196:197]
	v_pk_fma_f32 v[106:107], v[118:119], v[142:143], v[194:195]
	v_lshl_add_u64 v[74:75], s[14:15], 0, v[168:169]
	v_pk_fma_f32 v[92:93], v[104:105], v[144:145], v[212:213]
	v_pk_fma_f32 v[90:91], v[102:103], v[142:143], v[210:211]
	global_store_dwordx4 v[94:95], v[78:81], off offset:512
	v_pk_fma_f32 v[76:77], v[88:89], v[144:145], v[228:229]
	v_pk_fma_f32 v[132:133], v[132:133], v[144:145], v[180:181]
	v_lshl_add_u64 v[78:79], v[74:75], 0, v[158:159]
	v_pk_fma_f32 v[74:75], v[86:87], v[142:143], v[226:227]
	v_pk_fma_f32 v[130:131], v[130:131], v[142:143], v[178:179]
	v_pk_fma_f32 v[124:125], v[124:125], v[140:141], v[184:185]
	v_pk_fma_f32 v[122:123], v[122:123], v[138:139], v[182:183]
	global_store_dwordx4 v[110:111], v[106:109], off
	global_store_dwordx4 v[94:95], v[90:93], off
	global_store_dwordx4 v[78:79], v[74:77], off
	v_pk_fma_f32 v[108:109], v[116:117], v[140:141], v[200:201]
	v_pk_fma_f32 v[106:107], v[114:115], v[138:139], v[198:199]
	v_pk_fma_f32 v[92:93], v[100:101], v[140:141], v[216:217]
	v_pk_fma_f32 v[90:91], v[98:99], v[138:139], v[214:215]
	v_pk_fma_f32 v[76:77], v[84:85], v[140:141], v[232:233]
	v_pk_fma_f32 v[74:75], v[82:83], v[138:139], v[230:231]
	v_pk_fma_f32 v[72:73], v[72:73], v[136:137], v[236:237]
	v_pk_fma_f32 v[70:71], v[70:71], v[134:135], v[234:235]
	v_pk_fma_f32 v[68:69], v[68:69], v[128:129], v[240:241]
	v_pk_fma_f32 v[66:67], v[66:67], v[126:127], v[238:239]
	v_lshl_add_u64 v[168:169], v[162:163], 0, s[22:23]
	global_store_dwordx4 v[246:247], v[130:133], off
	global_store_dwordx4 v[246:247], v[122:125], off offset:64
	global_store_dwordx4 v[110:111], v[106:109], off offset:64
	global_store_dwordx4 v[94:95], v[90:93], off offset:64
	global_store_dwordx4 v[78:79], v[74:77], off offset:64
	global_store_dwordx4 v[78:79], v[70:73], off offset:512
	global_store_dwordx4 v[78:79], v[66:69], off offset:576
	v_lshl_add_u64 v[182:183], v[162:163], 0, s[24:25]
	v_lshl_add_u64 v[108:109], v[162:163], 0, s[26:27]
	v_lshl_add_u64 v[66:67], v[160:161], 0, v[168:169]
	global_load_dwordx4 v[110:113], v[66:67], off
	global_load_dwordx4 v[114:117], v[66:67], off offset:64
	global_load_dwordx4 v[118:121], v[66:67], off offset:512
	global_load_dwordx4 v[122:125], v[66:67], off offset:576
	v_lshl_add_u64 v[66:67], v[160:161], 0, v[182:183]
	global_load_dwordx4 v[130:133], v[66:67], off
	global_load_dwordx4 v[178:181], v[66:67], off offset:64
	global_load_dwordx4 v[102:105], v[66:67], off offset:512
	global_load_dwordx4 v[98:101], v[66:67], off offset:576
	v_lshl_add_u64 v[66:67], v[160:161], 0, v[108:109]
	v_lshl_add_u64 v[106:107], v[162:163], 0, s[16:17]
	global_load_dwordx4 v[94:97], v[66:67], off
	global_load_dwordx4 v[90:93], v[66:67], off offset:64
	global_load_dwordx4 v[86:89], v[66:67], off offset:512
	global_load_dwordx4 v[82:85], v[66:67], off offset:576
	v_lshl_add_u64 v[66:67], v[160:161], 0, v[106:107]
	global_load_dwordx4 v[78:81], v[66:67], off
	global_load_dwordx4 v[74:77], v[66:67], off offset:64
	global_load_dwordx4 v[70:73], v[66:67], off offset:512
	s_nop 0
	global_load_dwordx4 v[66:69], v[66:67], off offset:576
	v_lshl_add_u64 v[160:161], s[14:15], 0, v[168:169]
	v_lshl_add_u64 v[160:161], v[160:161], 0, v[158:159]
	s_waitcnt vmcnt(0)
	v_pk_fma_f32 v[44:45], v[44:45], v[128:129], v[124:125]
	v_pk_fma_f32 v[42:43], v[42:43], v[126:127], v[122:123]
	v_pk_fma_f32 v[52:53], v[52:53], v[136:137], v[120:121]
	v_pk_fma_f32 v[50:51], v[50:51], v[134:135], v[118:119]
	global_store_dwordx4 v[160:161], v[42:45], off offset:576
	global_store_dwordx4 v[160:161], v[50:53], off offset:512
	v_pk_fma_f32 v[28:29], v[28:29], v[128:129], v[100:101]
	v_lshl_add_u64 v[42:43], s[14:15], 0, v[182:183]
	v_lshl_add_u64 v[50:51], v[42:43], 0, v[158:159]
	v_pk_fma_f32 v[26:27], v[26:27], v[126:127], v[98:99]
	v_pk_fma_f32 v[36:37], v[36:37], v[136:137], v[104:105]
	v_pk_fma_f32 v[34:35], v[34:35], v[134:135], v[102:103]
	global_store_dwordx4 v[50:51], v[26:29], off offset:576
	global_store_dwordx4 v[50:51], v[34:37], off offset:512
	v_pk_fma_f32 v[12:13], v[12:13], v[128:129], v[84:85]
	v_lshl_add_u64 v[26:27], s[14:15], 0, v[108:109]
	v_lshl_add_u64 v[34:35], v[26:27], 0, v[158:159]
	v_pk_fma_f32 v[10:11], v[10:11], v[126:127], v[82:83]
	v_pk_fma_f32 v[20:21], v[20:21], v[136:137], v[88:89]
	v_pk_fma_f32 v[18:19], v[18:19], v[134:135], v[86:87]
	global_store_dwordx4 v[34:35], v[10:13], off offset:576
	v_pk_fma_f32 v[44:45], v[56:57], v[144:145], v[132:133]
	v_pk_fma_f32 v[42:43], v[54:55], v[142:143], v[130:131]
	v_lshl_add_u64 v[10:11], s[14:15], 0, v[106:107]
	v_pk_fma_f32 v[28:29], v[40:41], v[144:145], v[96:97]
	v_pk_fma_f32 v[26:27], v[38:39], v[142:143], v[94:95]
	global_store_dwordx4 v[34:35], v[18:21], off offset:512
	v_pk_fma_f32 v[12:13], v[24:25], v[144:145], v[80:81]
	v_pk_fma_f32 v[64:65], v[64:65], v[144:145], v[112:113]
	v_lshl_add_u64 v[18:19], v[10:11], 0, v[158:159]
	v_pk_fma_f32 v[10:11], v[22:23], v[142:143], v[78:79]
	v_pk_fma_f32 v[62:63], v[62:63], v[142:143], v[110:111]
	v_pk_fma_f32 v[60:61], v[60:61], v[140:141], v[116:117]
	v_pk_fma_f32 v[58:59], v[58:59], v[138:139], v[114:115]
	global_store_dwordx4 v[50:51], v[42:45], off
	global_store_dwordx4 v[34:35], v[26:29], off
	global_store_dwordx4 v[18:19], v[10:13], off
	v_pk_fma_f32 v[44:45], v[48:49], v[140:141], v[180:181]
	v_pk_fma_f32 v[42:43], v[46:47], v[138:139], v[178:179]
	v_pk_fma_f32 v[28:29], v[32:33], v[140:141], v[92:93]
	v_pk_fma_f32 v[26:27], v[30:31], v[138:139], v[90:91]
	v_pk_fma_f32 v[12:13], v[16:17], v[140:141], v[76:77]
	v_pk_fma_f32 v[10:11], v[14:15], v[138:139], v[74:75]
	v_pk_fma_f32 v[8:9], v[8:9], v[136:137], v[72:73]
	v_pk_fma_f32 v[6:7], v[6:7], v[134:135], v[70:71]
	v_pk_fma_f32 v[4:5], v[4:5], v[128:129], v[68:69]
	v_pk_fma_f32 v[2:3], v[2:3], v[126:127], v[66:67]
	s_and_b64 vcc, exec, s[4:5]
	s_mov_b32 s57, s54
	s_mov_b32 s56, s55
	s_mov_b64 s[30:31], s[8:9]
	s_mov_b64 s[28:29], s[6:7]
	global_store_dwordx4 v[160:161], v[62:65], off
	global_store_dwordx4 v[160:161], v[58:61], off offset:64
	global_store_dwordx4 v[50:51], v[42:45], off offset:64
	global_store_dwordx4 v[34:35], v[26:29], off offset:64
	global_store_dwordx4 v[18:19], v[10:13], off offset:64
	global_store_dwordx4 v[18:19], v[6:9], off offset:512
	global_store_dwordx4 v[18:19], v[2:5], off offset:576
	s_cbranch_vccz .LBB0_1286
	s_setprio 0
	s_waitcnt vmcnt(0)
	s_cmpk_gt_u32 s38, 0xff
	s_cbranch_scc1 .LBB0_1301
	s_barrier
